# RWKV scan process bodies hand-scheduled: packed f32 ops, 3-step LDS operand prefetch, paired y stores
# speedup vs baseline: 1.0310x; 1.0310x over previous
.LBB0_633:
	s_cmpk_lg_i32 s44, 0x2100
	s_cselect_b64 s[8:9], -1, 0
	v_cndmask_b32_e64 v0, 0, 1, s[8:9]
	v_cmp_ne_u32_e64 s[8:9], 1, v0
	s_and_saveexec_b64 s[34:35], s[2:3]
	s_xor_b64 s[50:51], exec, s[34:35]
	s_cbranch_execz .LBB0_636
	s_and_b64 vcc, exec, s[8:9]
	s_cbranch_vccnz .LBB0_636
	ds_read_b128 v[22:25], v53 offset:768
	ds_read_b32 v128, v65 offset:1280
	ds_read_b128 v[14:17], v53 offset:256
	ds_read_b128 v[10:13], v53
	ds_read_b128 v[18:21], v53 offset:512
	ds_read_b128 v[108:111], v53 offset:1024
	ds_read_b128 v[124:127], v53 offset:2112
	ds_read_b32 v154, v65 offset:2624
	ds_read_b128 v[116:119], v53 offset:1600
	ds_read_b128 v[112:115], v53 offset:1344
	ds_read_b128 v[120:123], v53 offset:1856
	ds_read_b128 v[134:137], v53 offset:2368
	ds_read_b128 v[150:153], v53 offset:3456
	ds_read_b32 v214, v65 offset:3968
	ds_read_b128 v[142:145], v53 offset:2944
	ds_read_b128 v[138:141], v53 offset:2688
	ds_read_b128 v[146:149], v53 offset:3200
	ds_read_b128 v[182:185], v53 offset:3712
	s_waitcnt lgkmcnt(12)
	v_pk_mul_f32 v[22:23], v[22:23], v[128:129] op_sel_hi:[1,0]
	v_pk_mul_f32 v[24:25], v[24:25], v[128:129] op_sel_hi:[1,0]
	v_pk_mul_f32 v[88:89], v[86:87], v[14:15]
	v_pk_fma_f32 v[22:23], v[86:87], v[10:11], v[22:23]
	v_pk_fma_f32 v[88:89], v[84:85], v[16:17], v[88:89]
	s_nop 0
	v_add_f32_e32 v0, v88, v89
	v_pk_fma_f32 v[24:25], v[84:85], v[12:13], v[24:25]
	s_nop 0
	v_add_f32_dpp v0, v0, v0 row_ror:8 row_mask:0xf bank_mask:0xf bound_ctrl:1
	s_waitcnt lgkmcnt(0)
	v_pk_mul_f32 v[124:125], v[124:125], v[154:155] op_sel_hi:[1,0]
	v_add_f32_dpp v0, v0, v0 row_ror:4 row_mask:0xf bank_mask:0xf bound_ctrl:1
	v_pk_mul_f32 v[126:127], v[126:127], v[154:155] op_sel_hi:[1,0]
	ds_read_b128 v[206:209], v53 offset:4800
	ds_read_b32 v216, v65 offset:5312
	ds_read_b128 v[198:201], v53 offset:4288
	v_add_f32_dpp v0, v0, v0 row_ror:2 row_mask:0xf bank_mask:0xf bound_ctrl:1
	ds_read_b128 v[194:197], v53 offset:4032
	ds_read_b128 v[202:205], v53 offset:4544
	ds_read_b128 v[210:213], v53 offset:5056
	v_add_f32_dpp v0, v0, v0 row_ror:1 row_mask:0xf bank_mask:0xf bound_ctrl:1
	v_pk_fma_f32 v[86:87], v[0:1], v[18:19], v[22:23] op_sel_hi:[0,1,1]
	v_pk_fma_f32 v[84:85], v[0:1], v[20:21], v[24:25] op_sel_hi:[0,1,1]
	v_pk_mul_f32 v[88:89], v[86:87], v[116:117]
	v_pk_fma_f32 v[124:125], v[86:87], v[112:113], v[124:125]
	v_pk_fma_f32 v[88:89], v[84:85], v[118:119], v[88:89]
	v_pk_mul_f32 v[186:187], v[86:87], v[108:109]
	v_add_f32_e32 v0, v88, v89
	v_pk_fma_f32 v[126:127], v[84:85], v[114:115], v[126:127]
	v_pk_fma_f32 v[186:187], v[84:85], v[110:111], v[186:187]
	v_add_f32_dpp v0, v0, v0 row_ror:8 row_mask:0xf bank_mask:0xf bound_ctrl:1
	s_waitcnt lgkmcnt(6)
	v_pk_mul_f32 v[150:151], v[150:151], v[214:215] op_sel_hi:[1,0]
	v_add_f32_e32 v218, v186, v187
	v_add_f32_dpp v0, v0, v0 row_ror:4 row_mask:0xf bank_mask:0xf bound_ctrl:1
	v_pk_mul_f32 v[152:153], v[152:153], v[214:215] op_sel_hi:[1,0]
	ds_read_b128 v[22:25], v53 offset:6144
	ds_read_b32 v128, v65 offset:6656
	ds_read_b128 v[14:17], v53 offset:5632
	v_add_f32_dpp v0, v0, v0 row_ror:2 row_mask:0xf bank_mask:0xf bound_ctrl:1
	ds_read_b128 v[10:13], v53 offset:5376
	ds_read_b128 v[18:21], v53 offset:5888
	ds_read_b128 v[108:111], v53 offset:6400
	v_add_f32_dpp v0, v0, v0 row_ror:1 row_mask:0xf bank_mask:0xf bound_ctrl:1
	v_pk_fma_f32 v[86:87], v[0:1], v[120:121], v[124:125] op_sel_hi:[0,1,1]
	v_pk_fma_f32 v[84:85], v[0:1], v[122:123], v[126:127] op_sel_hi:[0,1,1]
	v_pk_mul_f32 v[88:89], v[86:87], v[142:143]
	v_pk_fma_f32 v[150:151], v[86:87], v[138:139], v[150:151]
	v_pk_fma_f32 v[88:89], v[84:85], v[144:145], v[88:89]
	v_pk_mul_f32 v[186:187], v[86:87], v[134:135]
	v_add_f32_e32 v0, v88, v89
	v_pk_fma_f32 v[152:153], v[84:85], v[140:141], v[152:153]
	v_pk_fma_f32 v[186:187], v[84:85], v[136:137], v[186:187]
	v_add_f32_dpp v0, v0, v0 row_ror:8 row_mask:0xf bank_mask:0xf bound_ctrl:1
	s_waitcnt lgkmcnt(6)
	v_pk_mul_f32 v[206:207], v[206:207], v[216:217] op_sel_hi:[1,0]
	v_add_f32_e32 v219, v186, v187
	v_add_f32_dpp v0, v0, v0 row_ror:4 row_mask:0xf bank_mask:0xf bound_ctrl:1
	v_pk_mul_f32 v[208:209], v[208:209], v[216:217] op_sel_hi:[1,0]
	ds_write2st64_b32 v77, v218, v219 offset0:0 offset1:4
	ds_read_b128 v[124:127], v53 offset:7488
	ds_read_b32 v154, v65 offset:8000
	ds_read_b128 v[116:119], v53 offset:6976
	v_add_f32_dpp v0, v0, v0 row_ror:2 row_mask:0xf bank_mask:0xf bound_ctrl:1
	ds_read_b128 v[112:115], v53 offset:6720
	ds_read_b128 v[120:123], v53 offset:7232
	ds_read_b128 v[134:137], v53 offset:7744
	v_add_f32_dpp v0, v0, v0 row_ror:1 row_mask:0xf bank_mask:0xf bound_ctrl:1
	v_pk_fma_f32 v[86:87], v[0:1], v[146:147], v[150:151] op_sel_hi:[0,1,1]
	v_pk_fma_f32 v[84:85], v[0:1], v[148:149], v[152:153] op_sel_hi:[0,1,1]
	v_pk_mul_f32 v[88:89], v[86:87], v[198:199]
	v_pk_fma_f32 v[206:207], v[86:87], v[194:195], v[206:207]
	v_pk_fma_f32 v[88:89], v[84:85], v[200:201], v[88:89]
	v_pk_mul_f32 v[186:187], v[86:87], v[182:183]
	v_add_f32_e32 v0, v88, v89
	v_pk_fma_f32 v[208:209], v[84:85], v[196:197], v[208:209]
	v_pk_fma_f32 v[186:187], v[84:85], v[184:185], v[186:187]
	v_add_f32_dpp v0, v0, v0 row_ror:8 row_mask:0xf bank_mask:0xf bound_ctrl:1
	s_waitcnt lgkmcnt(7)
	v_pk_mul_f32 v[22:23], v[22:23], v[128:129] op_sel_hi:[1,0]
	v_add_f32_e32 v218, v186, v187
	v_add_f32_dpp v0, v0, v0 row_ror:4 row_mask:0xf bank_mask:0xf bound_ctrl:1
	v_pk_mul_f32 v[24:25], v[24:25], v[128:129] op_sel_hi:[1,0]
	ds_read_b128 v[150:153], v53 offset:8832
	ds_read_b32 v214, v65 offset:9344
	ds_read_b128 v[142:145], v53 offset:8320
	v_add_f32_dpp v0, v0, v0 row_ror:2 row_mask:0xf bank_mask:0xf bound_ctrl:1
	ds_read_b128 v[138:141], v53 offset:8064
	ds_read_b128 v[146:149], v53 offset:8576
	ds_read_b128 v[182:185], v53 offset:9088
	v_add_f32_dpp v0, v0, v0 row_ror:1 row_mask:0xf bank_mask:0xf bound_ctrl:1
	v_pk_fma_f32 v[86:87], v[0:1], v[202:203], v[206:207] op_sel_hi:[0,1,1]
	v_pk_fma_f32 v[84:85], v[0:1], v[204:205], v[208:209] op_sel_hi:[0,1,1]
	v_pk_mul_f32 v[88:89], v[86:87], v[14:15]
	v_pk_fma_f32 v[22:23], v[86:87], v[10:11], v[22:23]
	v_pk_fma_f32 v[88:89], v[84:85], v[16:17], v[88:89]
	v_pk_mul_f32 v[186:187], v[86:87], v[210:211]
	v_add_f32_e32 v0, v88, v89
	v_pk_fma_f32 v[24:25], v[84:85], v[12:13], v[24:25]
	v_pk_fma_f32 v[186:187], v[84:85], v[212:213], v[186:187]
	v_add_f32_dpp v0, v0, v0 row_ror:8 row_mask:0xf bank_mask:0xf bound_ctrl:1
	s_waitcnt lgkmcnt(6)
	v_pk_mul_f32 v[124:125], v[124:125], v[154:155] op_sel_hi:[1,0]
	v_add_f32_e32 v219, v186, v187
	v_add_f32_dpp v0, v0, v0 row_ror:4 row_mask:0xf bank_mask:0xf bound_ctrl:1
	v_pk_mul_f32 v[126:127], v[126:127], v[154:155] op_sel_hi:[1,0]
	ds_write2st64_b32 v77, v218, v219 offset0:8 offset1:12
	ds_read_b128 v[206:209], v53 offset:10176
	ds_read_b32 v216, v65 offset:10688
	ds_read_b128 v[198:201], v53 offset:9664
	v_add_f32_dpp v0, v0, v0 row_ror:2 row_mask:0xf bank_mask:0xf bound_ctrl:1
	ds_read_b128 v[194:197], v53 offset:9408
	ds_read_b128 v[202:205], v53 offset:9920
	ds_read_b128 v[210:213], v53 offset:10432
	v_add_f32_dpp v0, v0, v0 row_ror:1 row_mask:0xf bank_mask:0xf bound_ctrl:1
	v_pk_fma_f32 v[86:87], v[0:1], v[18:19], v[22:23] op_sel_hi:[0,1,1]
	v_pk_fma_f32 v[84:85], v[0:1], v[20:21], v[24:25] op_sel_hi:[0,1,1]
	v_pk_mul_f32 v[88:89], v[86:87], v[116:117]
	v_pk_fma_f32 v[124:125], v[86:87], v[112:113], v[124:125]
	v_pk_fma_f32 v[88:89], v[84:85], v[118:119], v[88:89]
	v_pk_mul_f32 v[186:187], v[86:87], v[108:109]
	v_add_f32_e32 v0, v88, v89
	v_pk_fma_f32 v[126:127], v[84:85], v[114:115], v[126:127]
	v_pk_fma_f32 v[186:187], v[84:85], v[110:111], v[186:187]
	v_add_f32_dpp v0, v0, v0 row_ror:8 row_mask:0xf bank_mask:0xf bound_ctrl:1
	s_waitcnt lgkmcnt(7)
	v_pk_mul_f32 v[150:151], v[150:151], v[214:215] op_sel_hi:[1,0]
	v_add_f32_e32 v218, v186, v187
	v_add_f32_dpp v0, v0, v0 row_ror:4 row_mask:0xf bank_mask:0xf bound_ctrl:1
	v_pk_mul_f32 v[152:153], v[152:153], v[214:215] op_sel_hi:[1,0]
	ds_read_b128 v[22:25], v53 offset:11520
	ds_read_b32 v128, v65 offset:12032
	ds_read_b128 v[14:17], v53 offset:11008
	v_add_f32_dpp v0, v0, v0 row_ror:2 row_mask:0xf bank_mask:0xf bound_ctrl:1
	ds_read_b128 v[10:13], v53 offset:10752
	ds_read_b128 v[18:21], v53 offset:11264
	ds_read_b128 v[108:111], v53 offset:11776
	v_add_f32_dpp v0, v0, v0 row_ror:1 row_mask:0xf bank_mask:0xf bound_ctrl:1
	v_pk_fma_f32 v[86:87], v[0:1], v[120:121], v[124:125] op_sel_hi:[0,1,1]
	v_pk_fma_f32 v[84:85], v[0:1], v[122:123], v[126:127] op_sel_hi:[0,1,1]
	v_pk_mul_f32 v[88:89], v[86:87], v[142:143]
	v_pk_fma_f32 v[150:151], v[86:87], v[138:139], v[150:151]
	v_pk_fma_f32 v[88:89], v[84:85], v[144:145], v[88:89]
	v_pk_mul_f32 v[186:187], v[86:87], v[134:135]
	v_add_f32_e32 v0, v88, v89
	v_pk_fma_f32 v[152:153], v[84:85], v[140:141], v[152:153]
	v_pk_fma_f32 v[186:187], v[84:85], v[136:137], v[186:187]
	v_add_f32_dpp v0, v0, v0 row_ror:8 row_mask:0xf bank_mask:0xf bound_ctrl:1
	s_waitcnt lgkmcnt(6)
	v_pk_mul_f32 v[206:207], v[206:207], v[216:217] op_sel_hi:[1,0]
	v_add_f32_e32 v219, v186, v187
	v_add_f32_dpp v0, v0, v0 row_ror:4 row_mask:0xf bank_mask:0xf bound_ctrl:1
	v_pk_mul_f32 v[208:209], v[208:209], v[216:217] op_sel_hi:[1,0]
	ds_write2st64_b32 v77, v218, v219 offset0:16 offset1:20
	ds_read_b128 v[124:127], v53 offset:12864
	ds_read_b32 v154, v65 offset:13376
	ds_read_b128 v[116:119], v53 offset:12352
	v_add_f32_dpp v0, v0, v0 row_ror:2 row_mask:0xf bank_mask:0xf bound_ctrl:1
	ds_read_b128 v[112:115], v53 offset:12096
	ds_read_b128 v[120:123], v53 offset:12608
	ds_read_b128 v[134:137], v53 offset:13120
	v_add_f32_dpp v0, v0, v0 row_ror:1 row_mask:0xf bank_mask:0xf bound_ctrl:1
	v_pk_fma_f32 v[86:87], v[0:1], v[146:147], v[150:151] op_sel_hi:[0,1,1]
	v_pk_fma_f32 v[84:85], v[0:1], v[148:149], v[152:153] op_sel_hi:[0,1,1]
	v_pk_mul_f32 v[88:89], v[86:87], v[198:199]
	v_pk_fma_f32 v[206:207], v[86:87], v[194:195], v[206:207]
	v_pk_fma_f32 v[88:89], v[84:85], v[200:201], v[88:89]
	v_pk_mul_f32 v[186:187], v[86:87], v[182:183]
	v_add_f32_e32 v0, v88, v89
	v_pk_fma_f32 v[208:209], v[84:85], v[196:197], v[208:209]
	v_pk_fma_f32 v[186:187], v[84:85], v[184:185], v[186:187]
	v_add_f32_dpp v0, v0, v0 row_ror:8 row_mask:0xf bank_mask:0xf bound_ctrl:1
	s_waitcnt lgkmcnt(7)
	v_pk_mul_f32 v[22:23], v[22:23], v[128:129] op_sel_hi:[1,0]
	v_add_f32_e32 v218, v186, v187
	v_add_f32_dpp v0, v0, v0 row_ror:4 row_mask:0xf bank_mask:0xf bound_ctrl:1
	v_pk_mul_f32 v[24:25], v[24:25], v[128:129] op_sel_hi:[1,0]
	ds_read_b128 v[150:153], v53 offset:14208
	ds_read_b32 v214, v65 offset:14720
	ds_read_b128 v[142:145], v53 offset:13696
	v_add_f32_dpp v0, v0, v0 row_ror:2 row_mask:0xf bank_mask:0xf bound_ctrl:1
	ds_read_b128 v[138:141], v53 offset:13440
	ds_read_b128 v[146:149], v53 offset:13952
	ds_read_b128 v[182:185], v53 offset:14464
	v_add_f32_dpp v0, v0, v0 row_ror:1 row_mask:0xf bank_mask:0xf bound_ctrl:1
	v_pk_fma_f32 v[86:87], v[0:1], v[202:203], v[206:207] op_sel_hi:[0,1,1]
	v_pk_fma_f32 v[84:85], v[0:1], v[204:205], v[208:209] op_sel_hi:[0,1,1]
	v_pk_mul_f32 v[88:89], v[86:87], v[14:15]
	v_pk_fma_f32 v[22:23], v[86:87], v[10:11], v[22:23]
	v_pk_fma_f32 v[88:89], v[84:85], v[16:17], v[88:89]
	v_pk_mul_f32 v[186:187], v[86:87], v[210:211]
	v_add_f32_e32 v0, v88, v89
	v_pk_fma_f32 v[24:25], v[84:85], v[12:13], v[24:25]
	v_pk_fma_f32 v[186:187], v[84:85], v[212:213], v[186:187]
	v_add_f32_dpp v0, v0, v0 row_ror:8 row_mask:0xf bank_mask:0xf bound_ctrl:1
	s_waitcnt lgkmcnt(6)
	v_pk_mul_f32 v[124:125], v[124:125], v[154:155] op_sel_hi:[1,0]
	v_add_f32_e32 v219, v186, v187
	v_add_f32_dpp v0, v0, v0 row_ror:4 row_mask:0xf bank_mask:0xf bound_ctrl:1
	v_pk_mul_f32 v[126:127], v[126:127], v[154:155] op_sel_hi:[1,0]
	ds_write2st64_b32 v77, v218, v219 offset0:24 offset1:28
	ds_read_b128 v[206:209], v53 offset:15552
	ds_read_b32 v216, v65 offset:16064
	ds_read_b128 v[198:201], v53 offset:15040
	v_add_f32_dpp v0, v0, v0 row_ror:2 row_mask:0xf bank_mask:0xf bound_ctrl:1
	ds_read_b128 v[194:197], v53 offset:14784
	ds_read_b128 v[202:205], v53 offset:15296
	ds_read_b128 v[210:213], v53 offset:15808
	v_add_f32_dpp v0, v0, v0 row_ror:1 row_mask:0xf bank_mask:0xf bound_ctrl:1
	v_pk_fma_f32 v[86:87], v[0:1], v[18:19], v[22:23] op_sel_hi:[0,1,1]
	v_pk_fma_f32 v[84:85], v[0:1], v[20:21], v[24:25] op_sel_hi:[0,1,1]
	v_pk_mul_f32 v[88:89], v[86:87], v[116:117]
	v_pk_fma_f32 v[124:125], v[86:87], v[112:113], v[124:125]
	v_pk_fma_f32 v[88:89], v[84:85], v[118:119], v[88:89]
	v_pk_mul_f32 v[186:187], v[86:87], v[108:109]
	v_add_f32_e32 v0, v88, v89
	v_pk_fma_f32 v[126:127], v[84:85], v[114:115], v[126:127]
	v_pk_fma_f32 v[186:187], v[84:85], v[110:111], v[186:187]
	v_add_f32_dpp v0, v0, v0 row_ror:8 row_mask:0xf bank_mask:0xf bound_ctrl:1
	s_waitcnt lgkmcnt(7)
	v_pk_mul_f32 v[150:151], v[150:151], v[214:215] op_sel_hi:[1,0]
	v_add_f32_e32 v218, v186, v187
	v_add_f32_dpp v0, v0, v0 row_ror:4 row_mask:0xf bank_mask:0xf bound_ctrl:1
	v_pk_mul_f32 v[152:153], v[152:153], v[214:215] op_sel_hi:[1,0]
	ds_read_b128 v[22:25], v53 offset:16896
	ds_read_b32 v128, v65 offset:17408
	ds_read_b128 v[14:17], v53 offset:16384
	v_add_f32_dpp v0, v0, v0 row_ror:2 row_mask:0xf bank_mask:0xf bound_ctrl:1
	ds_read_b128 v[10:13], v53 offset:16128
	ds_read_b128 v[18:21], v53 offset:16640
	ds_read_b128 v[108:111], v53 offset:17152
	v_add_f32_dpp v0, v0, v0 row_ror:1 row_mask:0xf bank_mask:0xf bound_ctrl:1
	v_pk_fma_f32 v[86:87], v[0:1], v[120:121], v[124:125] op_sel_hi:[0,1,1]
	v_pk_fma_f32 v[84:85], v[0:1], v[122:123], v[126:127] op_sel_hi:[0,1,1]
	v_pk_mul_f32 v[88:89], v[86:87], v[142:143]
	v_pk_fma_f32 v[150:151], v[86:87], v[138:139], v[150:151]
	v_pk_fma_f32 v[88:89], v[84:85], v[144:145], v[88:89]
	v_pk_mul_f32 v[186:187], v[86:87], v[134:135]
	v_add_f32_e32 v0, v88, v89
	v_pk_fma_f32 v[152:153], v[84:85], v[140:141], v[152:153]
	v_pk_fma_f32 v[186:187], v[84:85], v[136:137], v[186:187]
	v_add_f32_dpp v0, v0, v0 row_ror:8 row_mask:0xf bank_mask:0xf bound_ctrl:1
	s_waitcnt lgkmcnt(6)
	v_pk_mul_f32 v[206:207], v[206:207], v[216:217] op_sel_hi:[1,0]
	v_add_f32_e32 v219, v186, v187
	v_add_f32_dpp v0, v0, v0 row_ror:4 row_mask:0xf bank_mask:0xf bound_ctrl:1
	v_pk_mul_f32 v[208:209], v[208:209], v[216:217] op_sel_hi:[1,0]
	ds_write2st64_b32 v77, v218, v219 offset0:32 offset1:36
	ds_read_b128 v[124:127], v53 offset:18240
	ds_read_b32 v154, v65 offset:18752
	ds_read_b128 v[116:119], v53 offset:17728
	v_add_f32_dpp v0, v0, v0 row_ror:2 row_mask:0xf bank_mask:0xf bound_ctrl:1
	ds_read_b128 v[112:115], v53 offset:17472
	ds_read_b128 v[120:123], v53 offset:17984
	ds_read_b128 v[134:137], v53 offset:18496
	v_add_f32_dpp v0, v0, v0 row_ror:1 row_mask:0xf bank_mask:0xf bound_ctrl:1
	v_pk_fma_f32 v[86:87], v[0:1], v[146:147], v[150:151] op_sel_hi:[0,1,1]
	v_pk_fma_f32 v[84:85], v[0:1], v[148:149], v[152:153] op_sel_hi:[0,1,1]
	v_pk_mul_f32 v[88:89], v[86:87], v[198:199]
	v_pk_fma_f32 v[206:207], v[86:87], v[194:195], v[206:207]
	v_pk_fma_f32 v[88:89], v[84:85], v[200:201], v[88:89]
	v_pk_mul_f32 v[186:187], v[86:87], v[182:183]
	v_add_f32_e32 v0, v88, v89
	v_pk_fma_f32 v[208:209], v[84:85], v[196:197], v[208:209]
	v_pk_fma_f32 v[186:187], v[84:85], v[184:185], v[186:187]
	v_add_f32_dpp v0, v0, v0 row_ror:8 row_mask:0xf bank_mask:0xf bound_ctrl:1
	s_waitcnt lgkmcnt(7)
	v_pk_mul_f32 v[22:23], v[22:23], v[128:129] op_sel_hi:[1,0]
	v_add_f32_e32 v218, v186, v187
	v_add_f32_dpp v0, v0, v0 row_ror:4 row_mask:0xf bank_mask:0xf bound_ctrl:1
	v_pk_mul_f32 v[24:25], v[24:25], v[128:129] op_sel_hi:[1,0]
	ds_read_b128 v[150:153], v53 offset:19584
	ds_read_b32 v214, v65 offset:20096
	ds_read_b128 v[142:145], v53 offset:19072
	v_add_f32_dpp v0, v0, v0 row_ror:2 row_mask:0xf bank_mask:0xf bound_ctrl:1
	ds_read_b128 v[138:141], v53 offset:18816
	ds_read_b128 v[146:149], v53 offset:19328
	ds_read_b128 v[182:185], v53 offset:19840
	v_add_f32_dpp v0, v0, v0 row_ror:1 row_mask:0xf bank_mask:0xf bound_ctrl:1
	v_pk_fma_f32 v[86:87], v[0:1], v[202:203], v[206:207] op_sel_hi:[0,1,1]
	v_pk_fma_f32 v[84:85], v[0:1], v[204:205], v[208:209] op_sel_hi:[0,1,1]
	v_pk_mul_f32 v[88:89], v[86:87], v[14:15]
	v_pk_fma_f32 v[22:23], v[86:87], v[10:11], v[22:23]
	v_pk_fma_f32 v[88:89], v[84:85], v[16:17], v[88:89]
	v_pk_mul_f32 v[186:187], v[86:87], v[210:211]
	v_add_f32_e32 v0, v88, v89
	v_pk_fma_f32 v[24:25], v[84:85], v[12:13], v[24:25]
	v_pk_fma_f32 v[186:187], v[84:85], v[212:213], v[186:187]
	v_add_f32_dpp v0, v0, v0 row_ror:8 row_mask:0xf bank_mask:0xf bound_ctrl:1
	s_waitcnt lgkmcnt(6)
	v_pk_mul_f32 v[124:125], v[124:125], v[154:155] op_sel_hi:[1,0]
	v_add_f32_e32 v219, v186, v187
	v_add_f32_dpp v0, v0, v0 row_ror:4 row_mask:0xf bank_mask:0xf bound_ctrl:1
	v_pk_mul_f32 v[126:127], v[126:127], v[154:155] op_sel_hi:[1,0]
	ds_write2st64_b32 v77, v218, v219 offset0:40 offset1:44
	ds_read_b128 v[206:209], v53 offset:20928
	ds_read_b32 v216, v65 offset:21440
	ds_read_b128 v[198:201], v53 offset:20416
	v_add_f32_dpp v0, v0, v0 row_ror:2 row_mask:0xf bank_mask:0xf bound_ctrl:1
	ds_read_b128 v[194:197], v53 offset:20160
	ds_read_b128 v[202:205], v53 offset:20672
	ds_read_b128 v[210:213], v53 offset:21184
	v_add_f32_dpp v0, v0, v0 row_ror:1 row_mask:0xf bank_mask:0xf bound_ctrl:1
	v_pk_fma_f32 v[86:87], v[0:1], v[18:19], v[22:23] op_sel_hi:[0,1,1]
	v_pk_fma_f32 v[84:85], v[0:1], v[20:21], v[24:25] op_sel_hi:[0,1,1]
	v_pk_mul_f32 v[88:89], v[86:87], v[116:117]
	v_pk_fma_f32 v[124:125], v[86:87], v[112:113], v[124:125]
	v_pk_fma_f32 v[88:89], v[84:85], v[118:119], v[88:89]
	v_pk_mul_f32 v[186:187], v[86:87], v[108:109]
	v_add_f32_e32 v0, v88, v89
	v_pk_fma_f32 v[126:127], v[84:85], v[114:115], v[126:127]
	v_pk_fma_f32 v[186:187], v[84:85], v[110:111], v[186:187]
	v_add_f32_dpp v0, v0, v0 row_ror:8 row_mask:0xf bank_mask:0xf bound_ctrl:1
	s_waitcnt lgkmcnt(7)
	v_pk_mul_f32 v[150:151], v[150:151], v[214:215] op_sel_hi:[1,0]
	v_add_f32_e32 v218, v186, v187
	v_add_f32_dpp v0, v0, v0 row_ror:4 row_mask:0xf bank_mask:0xf bound_ctrl:1
	v_pk_mul_f32 v[152:153], v[152:153], v[214:215] op_sel_hi:[1,0]
	ds_read_b128 v[22:25], v53 offset:22272
	ds_read_b32 v128, v65 offset:22784
	ds_read_b128 v[14:17], v53 offset:21760
	v_add_f32_dpp v0, v0, v0 row_ror:2 row_mask:0xf bank_mask:0xf bound_ctrl:1
	ds_read_b128 v[10:13], v53 offset:21504
	ds_read_b128 v[18:21], v53 offset:22016
	ds_read_b128 v[108:111], v53 offset:22528
	v_add_f32_dpp v0, v0, v0 row_ror:1 row_mask:0xf bank_mask:0xf bound_ctrl:1
	v_pk_fma_f32 v[86:87], v[0:1], v[120:121], v[124:125] op_sel_hi:[0,1,1]
	v_pk_fma_f32 v[84:85], v[0:1], v[122:123], v[126:127] op_sel_hi:[0,1,1]
	v_pk_mul_f32 v[88:89], v[86:87], v[142:143]
	v_pk_fma_f32 v[150:151], v[86:87], v[138:139], v[150:151]
	v_pk_fma_f32 v[88:89], v[84:85], v[144:145], v[88:89]
	v_pk_mul_f32 v[186:187], v[86:87], v[134:135]
	v_add_f32_e32 v0, v88, v89
	v_pk_fma_f32 v[152:153], v[84:85], v[140:141], v[152:153]
	v_pk_fma_f32 v[186:187], v[84:85], v[136:137], v[186:187]
	v_add_f32_dpp v0, v0, v0 row_ror:8 row_mask:0xf bank_mask:0xf bound_ctrl:1
	s_waitcnt lgkmcnt(6)
	v_pk_mul_f32 v[206:207], v[206:207], v[216:217] op_sel_hi:[1,0]
	v_add_f32_e32 v219, v186, v187
	v_add_f32_dpp v0, v0, v0 row_ror:4 row_mask:0xf bank_mask:0xf bound_ctrl:1
	v_pk_mul_f32 v[208:209], v[208:209], v[216:217] op_sel_hi:[1,0]
	ds_write2st64_b32 v77, v218, v219 offset0:48 offset1:52
	ds_read_b128 v[124:127], v53 offset:23616
	ds_read_b32 v154, v65 offset:24128
	ds_read_b128 v[116:119], v53 offset:23104
	v_add_f32_dpp v0, v0, v0 row_ror:2 row_mask:0xf bank_mask:0xf bound_ctrl:1
	ds_read_b128 v[112:115], v53 offset:22848
	ds_read_b128 v[120:123], v53 offset:23360
	ds_read_b128 v[134:137], v53 offset:23872
	v_add_f32_dpp v0, v0, v0 row_ror:1 row_mask:0xf bank_mask:0xf bound_ctrl:1
	v_pk_fma_f32 v[86:87], v[0:1], v[146:147], v[150:151] op_sel_hi:[0,1,1]
	v_pk_fma_f32 v[84:85], v[0:1], v[148:149], v[152:153] op_sel_hi:[0,1,1]
	v_pk_mul_f32 v[88:89], v[86:87], v[198:199]
	v_pk_fma_f32 v[206:207], v[86:87], v[194:195], v[206:207]
	v_pk_fma_f32 v[88:89], v[84:85], v[200:201], v[88:89]
	v_pk_mul_f32 v[186:187], v[86:87], v[182:183]
	v_add_f32_e32 v0, v88, v89
	v_pk_fma_f32 v[208:209], v[84:85], v[196:197], v[208:209]
	v_pk_fma_f32 v[186:187], v[84:85], v[184:185], v[186:187]
	v_add_f32_dpp v0, v0, v0 row_ror:8 row_mask:0xf bank_mask:0xf bound_ctrl:1
	s_waitcnt lgkmcnt(7)
	v_pk_mul_f32 v[22:23], v[22:23], v[128:129] op_sel_hi:[1,0]
	v_add_f32_e32 v218, v186, v187
	v_add_f32_dpp v0, v0, v0 row_ror:4 row_mask:0xf bank_mask:0xf bound_ctrl:1
	v_pk_mul_f32 v[24:25], v[24:25], v[128:129] op_sel_hi:[1,0]
	ds_read_b128 v[150:153], v53 offset:24960
	ds_read_b32 v214, v65 offset:25472
	ds_read_b128 v[142:145], v53 offset:24448
	v_add_f32_dpp v0, v0, v0 row_ror:2 row_mask:0xf bank_mask:0xf bound_ctrl:1
	ds_read_b128 v[138:141], v53 offset:24192
	ds_read_b128 v[146:149], v53 offset:24704
	ds_read_b128 v[182:185], v53 offset:25216
	v_add_f32_dpp v0, v0, v0 row_ror:1 row_mask:0xf bank_mask:0xf bound_ctrl:1
	v_pk_fma_f32 v[86:87], v[0:1], v[202:203], v[206:207] op_sel_hi:[0,1,1]
	v_pk_fma_f32 v[84:85], v[0:1], v[204:205], v[208:209] op_sel_hi:[0,1,1]
	v_pk_mul_f32 v[88:89], v[86:87], v[14:15]
	v_pk_fma_f32 v[22:23], v[86:87], v[10:11], v[22:23]
	v_pk_fma_f32 v[88:89], v[84:85], v[16:17], v[88:89]
	v_pk_mul_f32 v[186:187], v[86:87], v[210:211]
	v_add_f32_e32 v0, v88, v89
	v_pk_fma_f32 v[24:25], v[84:85], v[12:13], v[24:25]
	v_pk_fma_f32 v[186:187], v[84:85], v[212:213], v[186:187]
	v_add_f32_dpp v0, v0, v0 row_ror:8 row_mask:0xf bank_mask:0xf bound_ctrl:1
	s_waitcnt lgkmcnt(6)
	v_pk_mul_f32 v[124:125], v[124:125], v[154:155] op_sel_hi:[1,0]
	v_add_f32_e32 v219, v186, v187
	v_add_f32_dpp v0, v0, v0 row_ror:4 row_mask:0xf bank_mask:0xf bound_ctrl:1
	v_pk_mul_f32 v[126:127], v[126:127], v[154:155] op_sel_hi:[1,0]
	ds_write2st64_b32 v77, v218, v219 offset0:56 offset1:60
	ds_read_b128 v[206:209], v53 offset:26304
	ds_read_b32 v216, v65 offset:26816
	ds_read_b128 v[198:201], v53 offset:25792
	v_add_f32_dpp v0, v0, v0 row_ror:2 row_mask:0xf bank_mask:0xf bound_ctrl:1
	ds_read_b128 v[194:197], v53 offset:25536
	ds_read_b128 v[202:205], v53 offset:26048
	ds_read_b128 v[210:213], v53 offset:26560
	v_add_f32_dpp v0, v0, v0 row_ror:1 row_mask:0xf bank_mask:0xf bound_ctrl:1
	v_pk_fma_f32 v[86:87], v[0:1], v[18:19], v[22:23] op_sel_hi:[0,1,1]
	v_pk_fma_f32 v[84:85], v[0:1], v[20:21], v[24:25] op_sel_hi:[0,1,1]
	v_pk_mul_f32 v[88:89], v[86:87], v[116:117]
	v_pk_fma_f32 v[124:125], v[86:87], v[112:113], v[124:125]
	v_pk_fma_f32 v[88:89], v[84:85], v[118:119], v[88:89]
	v_pk_mul_f32 v[186:187], v[86:87], v[108:109]
	v_add_f32_e32 v0, v88, v89
	v_pk_fma_f32 v[126:127], v[84:85], v[114:115], v[126:127]
	v_pk_fma_f32 v[186:187], v[84:85], v[110:111], v[186:187]
	v_add_f32_dpp v0, v0, v0 row_ror:8 row_mask:0xf bank_mask:0xf bound_ctrl:1
	s_waitcnt lgkmcnt(7)
	v_pk_mul_f32 v[150:151], v[150:151], v[214:215] op_sel_hi:[1,0]
	v_add_f32_e32 v218, v186, v187
	v_add_f32_dpp v0, v0, v0 row_ror:4 row_mask:0xf bank_mask:0xf bound_ctrl:1
	v_pk_mul_f32 v[152:153], v[152:153], v[214:215] op_sel_hi:[1,0]
	ds_read_b128 v[22:25], v53 offset:27648
	ds_read_b32 v128, v65 offset:28160
	ds_read_b128 v[14:17], v53 offset:27136
	v_add_f32_dpp v0, v0, v0 row_ror:2 row_mask:0xf bank_mask:0xf bound_ctrl:1
	ds_read_b128 v[10:13], v53 offset:26880
	ds_read_b128 v[18:21], v53 offset:27392
	ds_read_b128 v[108:111], v53 offset:27904
	v_add_f32_dpp v0, v0, v0 row_ror:1 row_mask:0xf bank_mask:0xf bound_ctrl:1
	v_pk_fma_f32 v[86:87], v[0:1], v[120:121], v[124:125] op_sel_hi:[0,1,1]
	v_pk_fma_f32 v[84:85], v[0:1], v[122:123], v[126:127] op_sel_hi:[0,1,1]
	v_pk_mul_f32 v[88:89], v[86:87], v[142:143]
	v_pk_fma_f32 v[150:151], v[86:87], v[138:139], v[150:151]
	v_pk_fma_f32 v[88:89], v[84:85], v[144:145], v[88:89]
	v_pk_mul_f32 v[186:187], v[86:87], v[134:135]
	v_add_f32_e32 v0, v88, v89
	v_pk_fma_f32 v[152:153], v[84:85], v[140:141], v[152:153]
	v_pk_fma_f32 v[186:187], v[84:85], v[136:137], v[186:187]
	v_add_f32_dpp v0, v0, v0 row_ror:8 row_mask:0xf bank_mask:0xf bound_ctrl:1
	s_waitcnt lgkmcnt(6)
	v_pk_mul_f32 v[206:207], v[206:207], v[216:217] op_sel_hi:[1,0]
	v_add_f32_e32 v219, v186, v187
	v_add_f32_dpp v0, v0, v0 row_ror:4 row_mask:0xf bank_mask:0xf bound_ctrl:1
	v_pk_mul_f32 v[208:209], v[208:209], v[216:217] op_sel_hi:[1,0]
	ds_write2st64_b32 v77, v218, v219 offset0:64 offset1:68
	ds_read_b128 v[124:127], v53 offset:28992
	ds_read_b32 v154, v65 offset:29504
	ds_read_b128 v[116:119], v53 offset:28480
	v_add_f32_dpp v0, v0, v0 row_ror:2 row_mask:0xf bank_mask:0xf bound_ctrl:1
	ds_read_b128 v[112:115], v53 offset:28224
	ds_read_b128 v[120:123], v53 offset:28736
	ds_read_b128 v[134:137], v53 offset:29248
	v_add_f32_dpp v0, v0, v0 row_ror:1 row_mask:0xf bank_mask:0xf bound_ctrl:1
	v_pk_fma_f32 v[86:87], v[0:1], v[146:147], v[150:151] op_sel_hi:[0,1,1]
	v_pk_fma_f32 v[84:85], v[0:1], v[148:149], v[152:153] op_sel_hi:[0,1,1]
	v_pk_mul_f32 v[88:89], v[86:87], v[198:199]
	v_pk_fma_f32 v[206:207], v[86:87], v[194:195], v[206:207]
	v_pk_fma_f32 v[88:89], v[84:85], v[200:201], v[88:89]
	v_pk_mul_f32 v[186:187], v[86:87], v[182:183]
	v_add_f32_e32 v0, v88, v89
	v_pk_fma_f32 v[208:209], v[84:85], v[196:197], v[208:209]
	v_pk_fma_f32 v[186:187], v[84:85], v[184:185], v[186:187]
	v_add_f32_dpp v0, v0, v0 row_ror:8 row_mask:0xf bank_mask:0xf bound_ctrl:1
	s_waitcnt lgkmcnt(7)
	v_pk_mul_f32 v[22:23], v[22:23], v[128:129] op_sel_hi:[1,0]
	v_add_f32_e32 v218, v186, v187
	v_add_f32_dpp v0, v0, v0 row_ror:4 row_mask:0xf bank_mask:0xf bound_ctrl:1
	v_pk_mul_f32 v[24:25], v[24:25], v[128:129] op_sel_hi:[1,0]
	ds_read_b128 v[150:153], v53 offset:30336
	ds_read_b32 v214, v65 offset:30848
	ds_read_b128 v[142:145], v53 offset:29824
	v_add_f32_dpp v0, v0, v0 row_ror:2 row_mask:0xf bank_mask:0xf bound_ctrl:1
	ds_read_b128 v[138:141], v53 offset:29568
	ds_read_b128 v[146:149], v53 offset:30080
	ds_read_b128 v[182:185], v53 offset:30592
	v_add_f32_dpp v0, v0, v0 row_ror:1 row_mask:0xf bank_mask:0xf bound_ctrl:1
	v_pk_fma_f32 v[86:87], v[0:1], v[202:203], v[206:207] op_sel_hi:[0,1,1]
	v_pk_fma_f32 v[84:85], v[0:1], v[204:205], v[208:209] op_sel_hi:[0,1,1]
	v_pk_mul_f32 v[88:89], v[86:87], v[14:15]
	v_pk_fma_f32 v[22:23], v[86:87], v[10:11], v[22:23]
	v_pk_fma_f32 v[88:89], v[84:85], v[16:17], v[88:89]
	v_pk_mul_f32 v[186:187], v[86:87], v[210:211]
	v_add_f32_e32 v0, v88, v89
	v_pk_fma_f32 v[24:25], v[84:85], v[12:13], v[24:25]
	v_pk_fma_f32 v[186:187], v[84:85], v[212:213], v[186:187]
	v_add_f32_dpp v0, v0, v0 row_ror:8 row_mask:0xf bank_mask:0xf bound_ctrl:1
	s_waitcnt lgkmcnt(6)
	v_pk_mul_f32 v[124:125], v[124:125], v[154:155] op_sel_hi:[1,0]
	v_add_f32_e32 v219, v186, v187
	v_add_f32_dpp v0, v0, v0 row_ror:4 row_mask:0xf bank_mask:0xf bound_ctrl:1
	v_pk_mul_f32 v[126:127], v[126:127], v[154:155] op_sel_hi:[1,0]
	ds_write2st64_b32 v77, v218, v219 offset0:72 offset1:76
	ds_read_b128 v[206:209], v53 offset:31680
	ds_read_b32 v216, v65 offset:32192
	ds_read_b128 v[198:201], v53 offset:31168
	v_add_f32_dpp v0, v0, v0 row_ror:2 row_mask:0xf bank_mask:0xf bound_ctrl:1
	ds_read_b128 v[194:197], v53 offset:30912
	ds_read_b128 v[202:205], v53 offset:31424
	ds_read_b128 v[210:213], v53 offset:31936
	v_add_f32_dpp v0, v0, v0 row_ror:1 row_mask:0xf bank_mask:0xf bound_ctrl:1
	v_pk_fma_f32 v[86:87], v[0:1], v[18:19], v[22:23] op_sel_hi:[0,1,1]
	v_pk_fma_f32 v[84:85], v[0:1], v[20:21], v[24:25] op_sel_hi:[0,1,1]
	v_pk_mul_f32 v[88:89], v[86:87], v[116:117]
	v_pk_fma_f32 v[124:125], v[86:87], v[112:113], v[124:125]
	v_pk_fma_f32 v[88:89], v[84:85], v[118:119], v[88:89]
	v_pk_mul_f32 v[186:187], v[86:87], v[108:109]
	v_add_f32_e32 v0, v88, v89
	v_pk_fma_f32 v[126:127], v[84:85], v[114:115], v[126:127]
	v_pk_fma_f32 v[186:187], v[84:85], v[110:111], v[186:187]
	v_add_f32_dpp v0, v0, v0 row_ror:8 row_mask:0xf bank_mask:0xf bound_ctrl:1
	s_waitcnt lgkmcnt(7)
	v_pk_mul_f32 v[150:151], v[150:151], v[214:215] op_sel_hi:[1,0]
	v_add_f32_e32 v218, v186, v187
	v_add_f32_dpp v0, v0, v0 row_ror:4 row_mask:0xf bank_mask:0xf bound_ctrl:1
	v_pk_mul_f32 v[152:153], v[152:153], v[214:215] op_sel_hi:[1,0]
	ds_read_b128 v[22:25], v53 offset:33024
	ds_read_b32 v128, v65 offset:33536
	ds_read_b128 v[14:17], v53 offset:32512
	v_add_f32_dpp v0, v0, v0 row_ror:2 row_mask:0xf bank_mask:0xf bound_ctrl:1
	ds_read_b128 v[10:13], v53 offset:32256
	ds_read_b128 v[18:21], v53 offset:32768
	ds_read_b128 v[108:111], v53 offset:33280
	v_add_f32_dpp v0, v0, v0 row_ror:1 row_mask:0xf bank_mask:0xf bound_ctrl:1
	v_pk_fma_f32 v[86:87], v[0:1], v[120:121], v[124:125] op_sel_hi:[0,1,1]
	v_pk_fma_f32 v[84:85], v[0:1], v[122:123], v[126:127] op_sel_hi:[0,1,1]
	v_pk_mul_f32 v[88:89], v[86:87], v[142:143]
	v_pk_fma_f32 v[150:151], v[86:87], v[138:139], v[150:151]
	v_pk_fma_f32 v[88:89], v[84:85], v[144:145], v[88:89]
	v_pk_mul_f32 v[186:187], v[86:87], v[134:135]
	v_add_f32_e32 v0, v88, v89
	v_pk_fma_f32 v[152:153], v[84:85], v[140:141], v[152:153]
	v_pk_fma_f32 v[186:187], v[84:85], v[136:137], v[186:187]
	v_add_f32_dpp v0, v0, v0 row_ror:8 row_mask:0xf bank_mask:0xf bound_ctrl:1
	s_waitcnt lgkmcnt(6)
	v_pk_mul_f32 v[206:207], v[206:207], v[216:217] op_sel_hi:[1,0]
	v_add_f32_e32 v219, v186, v187
	v_add_f32_dpp v0, v0, v0 row_ror:4 row_mask:0xf bank_mask:0xf bound_ctrl:1
	v_pk_mul_f32 v[208:209], v[208:209], v[216:217] op_sel_hi:[1,0]
	ds_write2st64_b32 v77, v218, v219 offset0:80 offset1:84
	ds_read_b128 v[124:127], v53 offset:34368
	ds_read_b32 v154, v65 offset:34880
	ds_read_b128 v[116:119], v53 offset:33856
	v_add_f32_dpp v0, v0, v0 row_ror:2 row_mask:0xf bank_mask:0xf bound_ctrl:1
	ds_read_b128 v[112:115], v53 offset:33600
	ds_read_b128 v[120:123], v53 offset:34112
	ds_read_b128 v[134:137], v53 offset:34624
	v_add_f32_dpp v0, v0, v0 row_ror:1 row_mask:0xf bank_mask:0xf bound_ctrl:1
	v_pk_fma_f32 v[86:87], v[0:1], v[146:147], v[150:151] op_sel_hi:[0,1,1]
	v_pk_fma_f32 v[84:85], v[0:1], v[148:149], v[152:153] op_sel_hi:[0,1,1]
	v_pk_mul_f32 v[88:89], v[86:87], v[198:199]
	v_pk_fma_f32 v[206:207], v[86:87], v[194:195], v[206:207]
	v_pk_fma_f32 v[88:89], v[84:85], v[200:201], v[88:89]
	v_pk_mul_f32 v[186:187], v[86:87], v[182:183]
	v_add_f32_e32 v0, v88, v89
	v_pk_fma_f32 v[208:209], v[84:85], v[196:197], v[208:209]
	v_pk_fma_f32 v[186:187], v[84:85], v[184:185], v[186:187]
	v_add_f32_dpp v0, v0, v0 row_ror:8 row_mask:0xf bank_mask:0xf bound_ctrl:1
	s_waitcnt lgkmcnt(7)
	v_pk_mul_f32 v[22:23], v[22:23], v[128:129] op_sel_hi:[1,0]
	v_add_f32_e32 v218, v186, v187
	v_add_f32_dpp v0, v0, v0 row_ror:4 row_mask:0xf bank_mask:0xf bound_ctrl:1
	v_pk_mul_f32 v[24:25], v[24:25], v[128:129] op_sel_hi:[1,0]
	ds_read_b128 v[150:153], v53 offset:35712
	ds_read_b32 v214, v65 offset:36224
	ds_read_b128 v[142:145], v53 offset:35200
	v_add_f32_dpp v0, v0, v0 row_ror:2 row_mask:0xf bank_mask:0xf bound_ctrl:1
	ds_read_b128 v[138:141], v53 offset:34944
	ds_read_b128 v[146:149], v53 offset:35456
	ds_read_b128 v[182:185], v53 offset:35968
	v_add_f32_dpp v0, v0, v0 row_ror:1 row_mask:0xf bank_mask:0xf bound_ctrl:1
	v_pk_fma_f32 v[86:87], v[0:1], v[202:203], v[206:207] op_sel_hi:[0,1,1]
	v_pk_fma_f32 v[84:85], v[0:1], v[204:205], v[208:209] op_sel_hi:[0,1,1]
	v_pk_mul_f32 v[88:89], v[86:87], v[14:15]
	v_pk_fma_f32 v[22:23], v[86:87], v[10:11], v[22:23]
	v_pk_fma_f32 v[88:89], v[84:85], v[16:17], v[88:89]
	v_pk_mul_f32 v[186:187], v[86:87], v[210:211]
	v_add_f32_e32 v0, v88, v89
	v_pk_fma_f32 v[24:25], v[84:85], v[12:13], v[24:25]
	v_pk_fma_f32 v[186:187], v[84:85], v[212:213], v[186:187]
	v_add_f32_dpp v0, v0, v0 row_ror:8 row_mask:0xf bank_mask:0xf bound_ctrl:1
	s_waitcnt lgkmcnt(6)
	v_pk_mul_f32 v[124:125], v[124:125], v[154:155] op_sel_hi:[1,0]
	v_add_f32_e32 v219, v186, v187
	v_add_f32_dpp v0, v0, v0 row_ror:4 row_mask:0xf bank_mask:0xf bound_ctrl:1
	v_pk_mul_f32 v[126:127], v[126:127], v[154:155] op_sel_hi:[1,0]
	ds_write2st64_b32 v77, v218, v219 offset0:88 offset1:92
	ds_read_b128 v[206:209], v53 offset:37056
	ds_read_b32 v216, v65 offset:37568
	ds_read_b128 v[198:201], v53 offset:36544
	v_add_f32_dpp v0, v0, v0 row_ror:2 row_mask:0xf bank_mask:0xf bound_ctrl:1
	ds_read_b128 v[194:197], v53 offset:36288
	ds_read_b128 v[202:205], v53 offset:36800
	ds_read_b128 v[210:213], v53 offset:37312
	v_add_f32_dpp v0, v0, v0 row_ror:1 row_mask:0xf bank_mask:0xf bound_ctrl:1
	v_pk_fma_f32 v[86:87], v[0:1], v[18:19], v[22:23] op_sel_hi:[0,1,1]
	v_pk_fma_f32 v[84:85], v[0:1], v[20:21], v[24:25] op_sel_hi:[0,1,1]
	v_pk_mul_f32 v[88:89], v[86:87], v[116:117]
	v_pk_fma_f32 v[124:125], v[86:87], v[112:113], v[124:125]
	v_pk_fma_f32 v[88:89], v[84:85], v[118:119], v[88:89]
	v_pk_mul_f32 v[186:187], v[86:87], v[108:109]
	v_add_f32_e32 v0, v88, v89
	v_pk_fma_f32 v[126:127], v[84:85], v[114:115], v[126:127]
	v_pk_fma_f32 v[186:187], v[84:85], v[110:111], v[186:187]
	v_add_f32_dpp v0, v0, v0 row_ror:8 row_mask:0xf bank_mask:0xf bound_ctrl:1
	s_waitcnt lgkmcnt(7)
	v_pk_mul_f32 v[150:151], v[150:151], v[214:215] op_sel_hi:[1,0]
	v_add_f32_e32 v218, v186, v187
	v_add_f32_dpp v0, v0, v0 row_ror:4 row_mask:0xf bank_mask:0xf bound_ctrl:1
	v_pk_mul_f32 v[152:153], v[152:153], v[214:215] op_sel_hi:[1,0]
	ds_read_b128 v[22:25], v53 offset:38400
	ds_read_b32 v128, v65 offset:38912
	ds_read_b128 v[14:17], v53 offset:37888
	v_add_f32_dpp v0, v0, v0 row_ror:2 row_mask:0xf bank_mask:0xf bound_ctrl:1
	ds_read_b128 v[10:13], v53 offset:37632
	ds_read_b128 v[18:21], v53 offset:38144
	ds_read_b128 v[108:111], v53 offset:38656
	v_add_f32_dpp v0, v0, v0 row_ror:1 row_mask:0xf bank_mask:0xf bound_ctrl:1
	v_pk_fma_f32 v[86:87], v[0:1], v[120:121], v[124:125] op_sel_hi:[0,1,1]
	v_pk_fma_f32 v[84:85], v[0:1], v[122:123], v[126:127] op_sel_hi:[0,1,1]
	v_pk_mul_f32 v[88:89], v[86:87], v[142:143]
	v_pk_fma_f32 v[150:151], v[86:87], v[138:139], v[150:151]
	v_pk_fma_f32 v[88:89], v[84:85], v[144:145], v[88:89]
	v_pk_mul_f32 v[186:187], v[86:87], v[134:135]
	v_add_f32_e32 v0, v88, v89
	v_pk_fma_f32 v[152:153], v[84:85], v[140:141], v[152:153]
	v_pk_fma_f32 v[186:187], v[84:85], v[136:137], v[186:187]
	v_add_f32_dpp v0, v0, v0 row_ror:8 row_mask:0xf bank_mask:0xf bound_ctrl:1
	s_waitcnt lgkmcnt(6)
	v_pk_mul_f32 v[206:207], v[206:207], v[216:217] op_sel_hi:[1,0]
	v_add_f32_e32 v219, v186, v187
	v_add_f32_dpp v0, v0, v0 row_ror:4 row_mask:0xf bank_mask:0xf bound_ctrl:1
	v_pk_mul_f32 v[208:209], v[208:209], v[216:217] op_sel_hi:[1,0]
	ds_write2st64_b32 v77, v218, v219 offset0:96 offset1:100
	ds_read_b128 v[124:127], v53 offset:39744
	ds_read_b32 v154, v65 offset:40256
	ds_read_b128 v[116:119], v53 offset:39232
	v_add_f32_dpp v0, v0, v0 row_ror:2 row_mask:0xf bank_mask:0xf bound_ctrl:1
	ds_read_b128 v[112:115], v53 offset:38976
	ds_read_b128 v[120:123], v53 offset:39488
	ds_read_b128 v[134:137], v53 offset:40000
	v_add_f32_dpp v0, v0, v0 row_ror:1 row_mask:0xf bank_mask:0xf bound_ctrl:1
	v_pk_fma_f32 v[86:87], v[0:1], v[146:147], v[150:151] op_sel_hi:[0,1,1]
	v_pk_fma_f32 v[84:85], v[0:1], v[148:149], v[152:153] op_sel_hi:[0,1,1]
	v_pk_mul_f32 v[88:89], v[86:87], v[198:199]
	v_pk_fma_f32 v[206:207], v[86:87], v[194:195], v[206:207]
	v_pk_fma_f32 v[88:89], v[84:85], v[200:201], v[88:89]
	v_pk_mul_f32 v[186:187], v[86:87], v[182:183]
	v_add_f32_e32 v0, v88, v89
	v_pk_fma_f32 v[208:209], v[84:85], v[196:197], v[208:209]
	v_pk_fma_f32 v[186:187], v[84:85], v[184:185], v[186:187]
	v_add_f32_dpp v0, v0, v0 row_ror:8 row_mask:0xf bank_mask:0xf bound_ctrl:1
	s_waitcnt lgkmcnt(7)
	v_pk_mul_f32 v[22:23], v[22:23], v[128:129] op_sel_hi:[1,0]
	v_add_f32_e32 v218, v186, v187
	v_add_f32_dpp v0, v0, v0 row_ror:4 row_mask:0xf bank_mask:0xf bound_ctrl:1
	v_pk_mul_f32 v[24:25], v[24:25], v[128:129] op_sel_hi:[1,0]
	ds_read_b128 v[150:153], v53 offset:41088
	ds_read_b32 v214, v65 offset:41600
	ds_read_b128 v[142:145], v53 offset:40576
	v_add_f32_dpp v0, v0, v0 row_ror:2 row_mask:0xf bank_mask:0xf bound_ctrl:1
	ds_read_b128 v[138:141], v53 offset:40320
	ds_read_b128 v[146:149], v53 offset:40832
	ds_read_b128 v[182:185], v53 offset:41344
	v_add_f32_dpp v0, v0, v0 row_ror:1 row_mask:0xf bank_mask:0xf bound_ctrl:1
	v_pk_fma_f32 v[86:87], v[0:1], v[202:203], v[206:207] op_sel_hi:[0,1,1]
	v_pk_fma_f32 v[84:85], v[0:1], v[204:205], v[208:209] op_sel_hi:[0,1,1]
	v_pk_mul_f32 v[88:89], v[86:87], v[14:15]
	v_pk_fma_f32 v[22:23], v[86:87], v[10:11], v[22:23]
	v_pk_fma_f32 v[88:89], v[84:85], v[16:17], v[88:89]
	v_pk_mul_f32 v[186:187], v[86:87], v[210:211]
	v_add_f32_e32 v0, v88, v89
	v_pk_fma_f32 v[24:25], v[84:85], v[12:13], v[24:25]
	v_pk_fma_f32 v[186:187], v[84:85], v[212:213], v[186:187]
	v_add_f32_dpp v0, v0, v0 row_ror:8 row_mask:0xf bank_mask:0xf bound_ctrl:1
	s_waitcnt lgkmcnt(6)
	v_pk_mul_f32 v[124:125], v[124:125], v[154:155] op_sel_hi:[1,0]
	v_add_f32_e32 v219, v186, v187
	v_add_f32_dpp v0, v0, v0 row_ror:4 row_mask:0xf bank_mask:0xf bound_ctrl:1
	v_pk_mul_f32 v[126:127], v[126:127], v[154:155] op_sel_hi:[1,0]
	ds_write2st64_b32 v77, v218, v219 offset0:104 offset1:108
	ds_read_b128 v[206:209], v53 offset:42432
	ds_read_b32 v216, v65 offset:42944
	ds_read_b128 v[198:201], v53 offset:41920
	v_add_f32_dpp v0, v0, v0 row_ror:2 row_mask:0xf bank_mask:0xf bound_ctrl:1
	ds_read_b128 v[194:197], v53 offset:41664
	ds_read_b128 v[202:205], v53 offset:42176
	ds_read_b128 v[210:213], v53 offset:42688
	v_add_f32_dpp v0, v0, v0 row_ror:1 row_mask:0xf bank_mask:0xf bound_ctrl:1
	v_pk_fma_f32 v[86:87], v[0:1], v[18:19], v[22:23] op_sel_hi:[0,1,1]
	v_pk_fma_f32 v[84:85], v[0:1], v[20:21], v[24:25] op_sel_hi:[0,1,1]
	v_pk_mul_f32 v[88:89], v[86:87], v[116:117]
	v_pk_fma_f32 v[124:125], v[86:87], v[112:113], v[124:125]
	v_pk_fma_f32 v[88:89], v[84:85], v[118:119], v[88:89]
	v_pk_mul_f32 v[186:187], v[86:87], v[108:109]
	v_add_f32_e32 v0, v88, v89
	v_pk_fma_f32 v[126:127], v[84:85], v[114:115], v[126:127]
	v_pk_fma_f32 v[186:187], v[84:85], v[110:111], v[186:187]
	v_add_f32_dpp v0, v0, v0 row_ror:8 row_mask:0xf bank_mask:0xf bound_ctrl:1
	s_waitcnt lgkmcnt(7)
	v_pk_mul_f32 v[150:151], v[150:151], v[214:215] op_sel_hi:[1,0]
	v_add_f32_e32 v218, v186, v187
	v_add_f32_dpp v0, v0, v0 row_ror:4 row_mask:0xf bank_mask:0xf bound_ctrl:1
	v_pk_mul_f32 v[152:153], v[152:153], v[214:215] op_sel_hi:[1,0]
	s_nop 0
	v_add_f32_dpp v0, v0, v0 row_ror:2 row_mask:0xf bank_mask:0xf bound_ctrl:1
	s_nop 1
	v_add_f32_dpp v0, v0, v0 row_ror:1 row_mask:0xf bank_mask:0xf bound_ctrl:1
	v_pk_fma_f32 v[86:87], v[0:1], v[120:121], v[124:125] op_sel_hi:[0,1,1]
	v_pk_fma_f32 v[84:85], v[0:1], v[122:123], v[126:127] op_sel_hi:[0,1,1]
	v_pk_mul_f32 v[88:89], v[86:87], v[142:143]
	v_pk_fma_f32 v[150:151], v[86:87], v[138:139], v[150:151]
	v_pk_fma_f32 v[88:89], v[84:85], v[144:145], v[88:89]
	v_pk_mul_f32 v[186:187], v[86:87], v[134:135]
	v_add_f32_e32 v0, v88, v89
	v_pk_fma_f32 v[152:153], v[84:85], v[140:141], v[152:153]
	v_pk_fma_f32 v[186:187], v[84:85], v[136:137], v[186:187]
	v_add_f32_dpp v0, v0, v0 row_ror:8 row_mask:0xf bank_mask:0xf bound_ctrl:1
	s_waitcnt lgkmcnt(0)
	v_pk_mul_f32 v[206:207], v[206:207], v[216:217] op_sel_hi:[1,0]
	v_add_f32_e32 v219, v186, v187
	v_add_f32_dpp v0, v0, v0 row_ror:4 row_mask:0xf bank_mask:0xf bound_ctrl:1
	v_pk_mul_f32 v[208:209], v[208:209], v[216:217] op_sel_hi:[1,0]
	ds_write2st64_b32 v77, v218, v219 offset0:112 offset1:116
	v_add_f32_dpp v0, v0, v0 row_ror:2 row_mask:0xf bank_mask:0xf bound_ctrl:1
	s_nop 1
	v_add_f32_dpp v0, v0, v0 row_ror:1 row_mask:0xf bank_mask:0xf bound_ctrl:1
	v_pk_fma_f32 v[86:87], v[0:1], v[146:147], v[150:151] op_sel_hi:[0,1,1]
	v_pk_fma_f32 v[84:85], v[0:1], v[148:149], v[152:153] op_sel_hi:[0,1,1]
	v_pk_mul_f32 v[88:89], v[86:87], v[198:199]
	v_pk_fma_f32 v[206:207], v[86:87], v[194:195], v[206:207]
	v_pk_fma_f32 v[88:89], v[84:85], v[200:201], v[88:89]
	v_pk_mul_f32 v[186:187], v[86:87], v[182:183]
	v_add_f32_e32 v0, v88, v89
	v_pk_fma_f32 v[208:209], v[84:85], v[196:197], v[208:209]
	v_pk_fma_f32 v[186:187], v[84:85], v[184:185], v[186:187]
	v_add_f32_dpp v0, v0, v0 row_ror:8 row_mask:0xf bank_mask:0xf bound_ctrl:1
	v_add_f32_e32 v218, v186, v187
	s_nop 0
	v_add_f32_dpp v0, v0, v0 row_ror:4 row_mask:0xf bank_mask:0xf bound_ctrl:1
	s_nop 1
	v_add_f32_dpp v0, v0, v0 row_ror:2 row_mask:0xf bank_mask:0xf bound_ctrl:1
	s_nop 1
	v_add_f32_dpp v0, v0, v0 row_ror:1 row_mask:0xf bank_mask:0xf bound_ctrl:1
	v_pk_fma_f32 v[86:87], v[0:1], v[202:203], v[206:207] op_sel_hi:[0,1,1]
	v_pk_fma_f32 v[84:85], v[0:1], v[204:205], v[208:209] op_sel_hi:[0,1,1]
	v_pk_mul_f32 v[186:187], v[86:87], v[210:211]
	s_nop 0
	v_pk_fma_f32 v[186:187], v[84:85], v[212:213], v[186:187]
	s_nop 0
	v_add_f32_e32 v219, v186, v187
	ds_write2st64_b32 v77, v218, v219 offset0:120 offset1:124

.LBB0_647:
	s_or_b64 exec, exec, s[34:35]
	s_waitcnt lgkmcnt(0)
	s_barrier
	s_and_saveexec_b64 s[34:35], s[2:3]
	s_xor_b64 s[50:51], exec, s[34:35]
	s_cbranch_execz .LBB0_650
	s_and_b64 vcc, exec, s[8:9]
	s_cbranch_vccnz .LBB0_650
	ds_read_b128 v[22:25], v96 offset:768
	ds_read_b32 v128, v97
	ds_read_b128 v[14:17], v96 offset:256
	ds_read_b128 v[10:13], v96
	ds_read_b128 v[18:21], v96 offset:512
	ds_read_b128 v[108:111], v96 offset:1024
	ds_read_b128 v[124:127], v96 offset:2112
	ds_read_b32 v154, v97 offset:1344
	ds_read_b128 v[116:119], v96 offset:1600
	ds_read_b128 v[112:115], v96 offset:1344
	ds_read_b128 v[120:123], v96 offset:1856
	ds_read_b128 v[134:137], v96 offset:2368
	ds_read_b128 v[150:153], v96 offset:3456
	ds_read_b32 v214, v97 offset:2688
	ds_read_b128 v[142:145], v96 offset:2944
	ds_read_b128 v[138:141], v96 offset:2688
	ds_read_b128 v[146:149], v96 offset:3200
	ds_read_b128 v[182:185], v96 offset:3712
	s_waitcnt lgkmcnt(12)
	v_pk_mul_f32 v[22:23], v[22:23], v[128:129] op_sel_hi:[1,0]
	v_pk_mul_f32 v[24:25], v[24:25], v[128:129] op_sel_hi:[1,0]
	v_pk_mul_f32 v[88:89], v[86:87], v[14:15]
	v_pk_fma_f32 v[22:23], v[86:87], v[10:11], v[22:23]
	v_pk_fma_f32 v[88:89], v[84:85], v[16:17], v[88:89]
	s_nop 0
	v_add_f32_e32 v0, v88, v89
	v_pk_fma_f32 v[24:25], v[84:85], v[12:13], v[24:25]
	s_nop 0
	v_add_f32_dpp v0, v0, v0 row_ror:8 row_mask:0xf bank_mask:0xf bound_ctrl:1
	s_waitcnt lgkmcnt(0)
	v_pk_mul_f32 v[124:125], v[124:125], v[154:155] op_sel_hi:[1,0]
	v_add_f32_dpp v0, v0, v0 row_ror:4 row_mask:0xf bank_mask:0xf bound_ctrl:1
	v_pk_mul_f32 v[126:127], v[126:127], v[154:155] op_sel_hi:[1,0]
	ds_read_b128 v[206:209], v96 offset:4800
	ds_read_b32 v216, v97 offset:4032
	ds_read_b128 v[198:201], v96 offset:4288
	v_add_f32_dpp v0, v0, v0 row_ror:2 row_mask:0xf bank_mask:0xf bound_ctrl:1
	ds_read_b128 v[194:197], v96 offset:4032
	ds_read_b128 v[202:205], v96 offset:4544
	ds_read_b128 v[210:213], v96 offset:5056
	v_add_f32_dpp v0, v0, v0 row_ror:1 row_mask:0xf bank_mask:0xf bound_ctrl:1
	v_pk_fma_f32 v[86:87], v[0:1], v[18:19], v[22:23] op_sel_hi:[0,1,1]
	v_pk_fma_f32 v[84:85], v[0:1], v[20:21], v[24:25] op_sel_hi:[0,1,1]
	v_pk_mul_f32 v[88:89], v[86:87], v[116:117]
	v_pk_fma_f32 v[124:125], v[86:87], v[112:113], v[124:125]
	v_pk_fma_f32 v[88:89], v[84:85], v[118:119], v[88:89]
	v_pk_mul_f32 v[186:187], v[86:87], v[108:109]
	v_add_f32_e32 v0, v88, v89
	v_pk_fma_f32 v[126:127], v[84:85], v[114:115], v[126:127]
	v_pk_fma_f32 v[186:187], v[84:85], v[110:111], v[186:187]
	v_add_f32_dpp v0, v0, v0 row_ror:8 row_mask:0xf bank_mask:0xf bound_ctrl:1
	s_waitcnt lgkmcnt(6)
	v_pk_mul_f32 v[150:151], v[150:151], v[214:215] op_sel_hi:[1,0]
	v_add_f32_e32 v218, v186, v187
	v_add_f32_dpp v0, v0, v0 row_ror:4 row_mask:0xf bank_mask:0xf bound_ctrl:1
	v_pk_mul_f32 v[152:153], v[152:153], v[214:215] op_sel_hi:[1,0]
	ds_read_b128 v[22:25], v96 offset:6144
	ds_read_b32 v128, v97 offset:5376
	ds_read_b128 v[14:17], v96 offset:5632
	v_add_f32_dpp v0, v0, v0 row_ror:2 row_mask:0xf bank_mask:0xf bound_ctrl:1
	ds_read_b128 v[10:13], v96 offset:5376
	ds_read_b128 v[18:21], v96 offset:5888
	ds_read_b128 v[108:111], v96 offset:6400
	v_add_f32_dpp v0, v0, v0 row_ror:1 row_mask:0xf bank_mask:0xf bound_ctrl:1
	v_pk_fma_f32 v[86:87], v[0:1], v[120:121], v[124:125] op_sel_hi:[0,1,1]
	v_pk_fma_f32 v[84:85], v[0:1], v[122:123], v[126:127] op_sel_hi:[0,1,1]
	v_pk_mul_f32 v[88:89], v[86:87], v[142:143]
	v_pk_fma_f32 v[150:151], v[86:87], v[138:139], v[150:151]
	v_pk_fma_f32 v[88:89], v[84:85], v[144:145], v[88:89]
	v_pk_mul_f32 v[186:187], v[86:87], v[134:135]
	v_add_f32_e32 v0, v88, v89
	v_pk_fma_f32 v[152:153], v[84:85], v[140:141], v[152:153]
	v_pk_fma_f32 v[186:187], v[84:85], v[136:137], v[186:187]
	v_add_f32_dpp v0, v0, v0 row_ror:8 row_mask:0xf bank_mask:0xf bound_ctrl:1
	s_waitcnt lgkmcnt(6)
	v_pk_mul_f32 v[206:207], v[206:207], v[216:217] op_sel_hi:[1,0]
	v_add_f32_e32 v219, v186, v187
	v_add_f32_dpp v0, v0, v0 row_ror:4 row_mask:0xf bank_mask:0xf bound_ctrl:1
	v_pk_mul_f32 v[208:209], v[208:209], v[216:217] op_sel_hi:[1,0]
	ds_write2st64_b32 v98, v218, v219 offset0:0 offset1:4
	ds_read_b128 v[124:127], v96 offset:7488
	ds_read_b32 v154, v97 offset:6720
	ds_read_b128 v[116:119], v96 offset:6976
	v_add_f32_dpp v0, v0, v0 row_ror:2 row_mask:0xf bank_mask:0xf bound_ctrl:1
	ds_read_b128 v[112:115], v96 offset:6720
	ds_read_b128 v[120:123], v96 offset:7232
	ds_read_b128 v[134:137], v96 offset:7744
	v_add_f32_dpp v0, v0, v0 row_ror:1 row_mask:0xf bank_mask:0xf bound_ctrl:1
	v_pk_fma_f32 v[86:87], v[0:1], v[146:147], v[150:151] op_sel_hi:[0,1,1]
	v_pk_fma_f32 v[84:85], v[0:1], v[148:149], v[152:153] op_sel_hi:[0,1,1]
	v_pk_mul_f32 v[88:89], v[86:87], v[198:199]
	v_pk_fma_f32 v[206:207], v[86:87], v[194:195], v[206:207]
	v_pk_fma_f32 v[88:89], v[84:85], v[200:201], v[88:89]
	v_pk_mul_f32 v[186:187], v[86:87], v[182:183]
	v_add_f32_e32 v0, v88, v89
	v_pk_fma_f32 v[208:209], v[84:85], v[196:197], v[208:209]
	v_pk_fma_f32 v[186:187], v[84:85], v[184:185], v[186:187]
	v_add_f32_dpp v0, v0, v0 row_ror:8 row_mask:0xf bank_mask:0xf bound_ctrl:1
	s_waitcnt lgkmcnt(7)
	v_pk_mul_f32 v[22:23], v[22:23], v[128:129] op_sel_hi:[1,0]
	v_add_f32_e32 v218, v186, v187
	v_add_f32_dpp v0, v0, v0 row_ror:4 row_mask:0xf bank_mask:0xf bound_ctrl:1
	v_pk_mul_f32 v[24:25], v[24:25], v[128:129] op_sel_hi:[1,0]
	ds_read_b128 v[150:153], v96 offset:8832
	ds_read_b32 v214, v97 offset:8064
	ds_read_b128 v[142:145], v96 offset:8320
	v_add_f32_dpp v0, v0, v0 row_ror:2 row_mask:0xf bank_mask:0xf bound_ctrl:1
	ds_read_b128 v[138:141], v96 offset:8064
	ds_read_b128 v[146:149], v96 offset:8576
	ds_read_b128 v[182:185], v96 offset:9088
	v_add_f32_dpp v0, v0, v0 row_ror:1 row_mask:0xf bank_mask:0xf bound_ctrl:1
	v_pk_fma_f32 v[86:87], v[0:1], v[202:203], v[206:207] op_sel_hi:[0,1,1]
	v_pk_fma_f32 v[84:85], v[0:1], v[204:205], v[208:209] op_sel_hi:[0,1,1]
	v_pk_mul_f32 v[88:89], v[86:87], v[14:15]
	v_pk_fma_f32 v[22:23], v[86:87], v[10:11], v[22:23]
	v_pk_fma_f32 v[88:89], v[84:85], v[16:17], v[88:89]
	v_pk_mul_f32 v[186:187], v[86:87], v[210:211]
	v_add_f32_e32 v0, v88, v89
	v_pk_fma_f32 v[24:25], v[84:85], v[12:13], v[24:25]
	v_pk_fma_f32 v[186:187], v[84:85], v[212:213], v[186:187]
	v_add_f32_dpp v0, v0, v0 row_ror:8 row_mask:0xf bank_mask:0xf bound_ctrl:1
	s_waitcnt lgkmcnt(6)
	v_pk_mul_f32 v[124:125], v[124:125], v[154:155] op_sel_hi:[1,0]
	v_add_f32_e32 v219, v186, v187
	v_add_f32_dpp v0, v0, v0 row_ror:4 row_mask:0xf bank_mask:0xf bound_ctrl:1
	v_pk_mul_f32 v[126:127], v[126:127], v[154:155] op_sel_hi:[1,0]
	ds_write2st64_b32 v98, v218, v219 offset0:8 offset1:12
	ds_read_b128 v[206:209], v96 offset:10176
	ds_read_b32 v216, v97 offset:9408
	ds_read_b128 v[198:201], v96 offset:9664
	v_add_f32_dpp v0, v0, v0 row_ror:2 row_mask:0xf bank_mask:0xf bound_ctrl:1
	ds_read_b128 v[194:197], v96 offset:9408
	ds_read_b128 v[202:205], v96 offset:9920
	ds_read_b128 v[210:213], v96 offset:10432
	v_add_f32_dpp v0, v0, v0 row_ror:1 row_mask:0xf bank_mask:0xf bound_ctrl:1
	v_pk_fma_f32 v[86:87], v[0:1], v[18:19], v[22:23] op_sel_hi:[0,1,1]
	v_pk_fma_f32 v[84:85], v[0:1], v[20:21], v[24:25] op_sel_hi:[0,1,1]
	v_pk_mul_f32 v[88:89], v[86:87], v[116:117]
	v_pk_fma_f32 v[124:125], v[86:87], v[112:113], v[124:125]
	v_pk_fma_f32 v[88:89], v[84:85], v[118:119], v[88:89]
	v_pk_mul_f32 v[186:187], v[86:87], v[108:109]
	v_add_f32_e32 v0, v88, v89
	v_pk_fma_f32 v[126:127], v[84:85], v[114:115], v[126:127]
	v_pk_fma_f32 v[186:187], v[84:85], v[110:111], v[186:187]
	v_add_f32_dpp v0, v0, v0 row_ror:8 row_mask:0xf bank_mask:0xf bound_ctrl:1
	s_waitcnt lgkmcnt(7)
	v_pk_mul_f32 v[150:151], v[150:151], v[214:215] op_sel_hi:[1,0]
	v_add_f32_e32 v218, v186, v187
	v_add_f32_dpp v0, v0, v0 row_ror:4 row_mask:0xf bank_mask:0xf bound_ctrl:1
	v_pk_mul_f32 v[152:153], v[152:153], v[214:215] op_sel_hi:[1,0]
	ds_read_b128 v[22:25], v96 offset:11520
	ds_read_b32 v128, v97 offset:10752
	ds_read_b128 v[14:17], v96 offset:11008
	v_add_f32_dpp v0, v0, v0 row_ror:2 row_mask:0xf bank_mask:0xf bound_ctrl:1
	ds_read_b128 v[10:13], v96 offset:10752
	ds_read_b128 v[18:21], v96 offset:11264
	ds_read_b128 v[108:111], v96 offset:11776
	v_add_f32_dpp v0, v0, v0 row_ror:1 row_mask:0xf bank_mask:0xf bound_ctrl:1
	v_pk_fma_f32 v[86:87], v[0:1], v[120:121], v[124:125] op_sel_hi:[0,1,1]
	v_pk_fma_f32 v[84:85], v[0:1], v[122:123], v[126:127] op_sel_hi:[0,1,1]
	v_pk_mul_f32 v[88:89], v[86:87], v[142:143]
	v_pk_fma_f32 v[150:151], v[86:87], v[138:139], v[150:151]
	v_pk_fma_f32 v[88:89], v[84:85], v[144:145], v[88:89]
	v_pk_mul_f32 v[186:187], v[86:87], v[134:135]
	v_add_f32_e32 v0, v88, v89
	v_pk_fma_f32 v[152:153], v[84:85], v[140:141], v[152:153]
	v_pk_fma_f32 v[186:187], v[84:85], v[136:137], v[186:187]
	v_add_f32_dpp v0, v0, v0 row_ror:8 row_mask:0xf bank_mask:0xf bound_ctrl:1
	s_waitcnt lgkmcnt(6)
	v_pk_mul_f32 v[206:207], v[206:207], v[216:217] op_sel_hi:[1,0]
	v_add_f32_e32 v219, v186, v187
	v_add_f32_dpp v0, v0, v0 row_ror:4 row_mask:0xf bank_mask:0xf bound_ctrl:1
	v_pk_mul_f32 v[208:209], v[208:209], v[216:217] op_sel_hi:[1,0]
	ds_write2st64_b32 v98, v218, v219 offset0:16 offset1:20
	ds_read_b128 v[124:127], v96 offset:12864
	ds_read_b32 v154, v97 offset:12096
	ds_read_b128 v[116:119], v96 offset:12352
	v_add_f32_dpp v0, v0, v0 row_ror:2 row_mask:0xf bank_mask:0xf bound_ctrl:1
	ds_read_b128 v[112:115], v96 offset:12096
	ds_read_b128 v[120:123], v96 offset:12608
	ds_read_b128 v[134:137], v96 offset:13120
	v_add_f32_dpp v0, v0, v0 row_ror:1 row_mask:0xf bank_mask:0xf bound_ctrl:1
	v_pk_fma_f32 v[86:87], v[0:1], v[146:147], v[150:151] op_sel_hi:[0,1,1]
	v_pk_fma_f32 v[84:85], v[0:1], v[148:149], v[152:153] op_sel_hi:[0,1,1]
	v_pk_mul_f32 v[88:89], v[86:87], v[198:199]
	v_pk_fma_f32 v[206:207], v[86:87], v[194:195], v[206:207]
	v_pk_fma_f32 v[88:89], v[84:85], v[200:201], v[88:89]
	v_pk_mul_f32 v[186:187], v[86:87], v[182:183]
	v_add_f32_e32 v0, v88, v89
	v_pk_fma_f32 v[208:209], v[84:85], v[196:197], v[208:209]
	v_pk_fma_f32 v[186:187], v[84:85], v[184:185], v[186:187]
	v_add_f32_dpp v0, v0, v0 row_ror:8 row_mask:0xf bank_mask:0xf bound_ctrl:1
	s_waitcnt lgkmcnt(7)
	v_pk_mul_f32 v[22:23], v[22:23], v[128:129] op_sel_hi:[1,0]
	v_add_f32_e32 v218, v186, v187
	v_add_f32_dpp v0, v0, v0 row_ror:4 row_mask:0xf bank_mask:0xf bound_ctrl:1
	v_pk_mul_f32 v[24:25], v[24:25], v[128:129] op_sel_hi:[1,0]
	ds_read_b128 v[150:153], v96 offset:14208
	ds_read_b32 v214, v97 offset:13440
	ds_read_b128 v[142:145], v96 offset:13696
	v_add_f32_dpp v0, v0, v0 row_ror:2 row_mask:0xf bank_mask:0xf bound_ctrl:1
	ds_read_b128 v[138:141], v96 offset:13440
	ds_read_b128 v[146:149], v96 offset:13952
	ds_read_b128 v[182:185], v96 offset:14464
	v_add_f32_dpp v0, v0, v0 row_ror:1 row_mask:0xf bank_mask:0xf bound_ctrl:1
	v_pk_fma_f32 v[86:87], v[0:1], v[202:203], v[206:207] op_sel_hi:[0,1,1]
	v_pk_fma_f32 v[84:85], v[0:1], v[204:205], v[208:209] op_sel_hi:[0,1,1]
	v_pk_mul_f32 v[88:89], v[86:87], v[14:15]
	v_pk_fma_f32 v[22:23], v[86:87], v[10:11], v[22:23]
	v_pk_fma_f32 v[88:89], v[84:85], v[16:17], v[88:89]
	v_pk_mul_f32 v[186:187], v[86:87], v[210:211]
	v_add_f32_e32 v0, v88, v89
	v_pk_fma_f32 v[24:25], v[84:85], v[12:13], v[24:25]
	v_pk_fma_f32 v[186:187], v[84:85], v[212:213], v[186:187]
	v_add_f32_dpp v0, v0, v0 row_ror:8 row_mask:0xf bank_mask:0xf bound_ctrl:1
	s_waitcnt lgkmcnt(6)
	v_pk_mul_f32 v[124:125], v[124:125], v[154:155] op_sel_hi:[1,0]
	v_add_f32_e32 v219, v186, v187
	v_add_f32_dpp v0, v0, v0 row_ror:4 row_mask:0xf bank_mask:0xf bound_ctrl:1
	v_pk_mul_f32 v[126:127], v[126:127], v[154:155] op_sel_hi:[1,0]
	ds_write2st64_b32 v98, v218, v219 offset0:24 offset1:28
	ds_read_b128 v[206:209], v96 offset:15552
	ds_read_b32 v216, v97 offset:14784
	ds_read_b128 v[198:201], v96 offset:15040
	v_add_f32_dpp v0, v0, v0 row_ror:2 row_mask:0xf bank_mask:0xf bound_ctrl:1
	ds_read_b128 v[194:197], v96 offset:14784
	ds_read_b128 v[202:205], v96 offset:15296
	ds_read_b128 v[210:213], v96 offset:15808
	v_add_f32_dpp v0, v0, v0 row_ror:1 row_mask:0xf bank_mask:0xf bound_ctrl:1
	v_pk_fma_f32 v[86:87], v[0:1], v[18:19], v[22:23] op_sel_hi:[0,1,1]
	v_pk_fma_f32 v[84:85], v[0:1], v[20:21], v[24:25] op_sel_hi:[0,1,1]
	v_pk_mul_f32 v[88:89], v[86:87], v[116:117]
	v_pk_fma_f32 v[124:125], v[86:87], v[112:113], v[124:125]
	v_pk_fma_f32 v[88:89], v[84:85], v[118:119], v[88:89]
	v_pk_mul_f32 v[186:187], v[86:87], v[108:109]
	v_add_f32_e32 v0, v88, v89
	v_pk_fma_f32 v[126:127], v[84:85], v[114:115], v[126:127]
	v_pk_fma_f32 v[186:187], v[84:85], v[110:111], v[186:187]
	v_add_f32_dpp v0, v0, v0 row_ror:8 row_mask:0xf bank_mask:0xf bound_ctrl:1
	s_waitcnt lgkmcnt(7)
	v_pk_mul_f32 v[150:151], v[150:151], v[214:215] op_sel_hi:[1,0]
	v_add_f32_e32 v218, v186, v187
	v_add_f32_dpp v0, v0, v0 row_ror:4 row_mask:0xf bank_mask:0xf bound_ctrl:1
	v_pk_mul_f32 v[152:153], v[152:153], v[214:215] op_sel_hi:[1,0]
	ds_read_b128 v[22:25], v96 offset:16896
	ds_read_b32 v128, v97 offset:16128
	ds_read_b128 v[14:17], v96 offset:16384
	v_add_f32_dpp v0, v0, v0 row_ror:2 row_mask:0xf bank_mask:0xf bound_ctrl:1
	ds_read_b128 v[10:13], v96 offset:16128
	ds_read_b128 v[18:21], v96 offset:16640
	ds_read_b128 v[108:111], v96 offset:17152
	v_add_f32_dpp v0, v0, v0 row_ror:1 row_mask:0xf bank_mask:0xf bound_ctrl:1
	v_pk_fma_f32 v[86:87], v[0:1], v[120:121], v[124:125] op_sel_hi:[0,1,1]
	v_pk_fma_f32 v[84:85], v[0:1], v[122:123], v[126:127] op_sel_hi:[0,1,1]
	v_pk_mul_f32 v[88:89], v[86:87], v[142:143]
	v_pk_fma_f32 v[150:151], v[86:87], v[138:139], v[150:151]
	v_pk_fma_f32 v[88:89], v[84:85], v[144:145], v[88:89]
	v_pk_mul_f32 v[186:187], v[86:87], v[134:135]
	v_add_f32_e32 v0, v88, v89
	v_pk_fma_f32 v[152:153], v[84:85], v[140:141], v[152:153]
	v_pk_fma_f32 v[186:187], v[84:85], v[136:137], v[186:187]
	v_add_f32_dpp v0, v0, v0 row_ror:8 row_mask:0xf bank_mask:0xf bound_ctrl:1
	s_waitcnt lgkmcnt(6)
	v_pk_mul_f32 v[206:207], v[206:207], v[216:217] op_sel_hi:[1,0]
	v_add_f32_e32 v219, v186, v187
	v_add_f32_dpp v0, v0, v0 row_ror:4 row_mask:0xf bank_mask:0xf bound_ctrl:1
	v_pk_mul_f32 v[208:209], v[208:209], v[216:217] op_sel_hi:[1,0]
	ds_write2st64_b32 v98, v218, v219 offset0:32 offset1:36
	ds_read_b128 v[124:127], v96 offset:18240
	ds_read_b32 v154, v97 offset:17472
	ds_read_b128 v[116:119], v96 offset:17728
	v_add_f32_dpp v0, v0, v0 row_ror:2 row_mask:0xf bank_mask:0xf bound_ctrl:1
	ds_read_b128 v[112:115], v96 offset:17472
	ds_read_b128 v[120:123], v96 offset:17984
	ds_read_b128 v[134:137], v96 offset:18496
	v_add_f32_dpp v0, v0, v0 row_ror:1 row_mask:0xf bank_mask:0xf bound_ctrl:1
	v_pk_fma_f32 v[86:87], v[0:1], v[146:147], v[150:151] op_sel_hi:[0,1,1]
	v_pk_fma_f32 v[84:85], v[0:1], v[148:149], v[152:153] op_sel_hi:[0,1,1]
	v_pk_mul_f32 v[88:89], v[86:87], v[198:199]
	v_pk_fma_f32 v[206:207], v[86:87], v[194:195], v[206:207]
	v_pk_fma_f32 v[88:89], v[84:85], v[200:201], v[88:89]
	v_pk_mul_f32 v[186:187], v[86:87], v[182:183]
	v_add_f32_e32 v0, v88, v89
	v_pk_fma_f32 v[208:209], v[84:85], v[196:197], v[208:209]
	v_pk_fma_f32 v[186:187], v[84:85], v[184:185], v[186:187]
	v_add_f32_dpp v0, v0, v0 row_ror:8 row_mask:0xf bank_mask:0xf bound_ctrl:1
	s_waitcnt lgkmcnt(7)
	v_pk_mul_f32 v[22:23], v[22:23], v[128:129] op_sel_hi:[1,0]
	v_add_f32_e32 v218, v186, v187
	v_add_f32_dpp v0, v0, v0 row_ror:4 row_mask:0xf bank_mask:0xf bound_ctrl:1
	v_pk_mul_f32 v[24:25], v[24:25], v[128:129] op_sel_hi:[1,0]
	ds_read_b128 v[150:153], v96 offset:19584
	ds_read_b32 v214, v97 offset:18816
	ds_read_b128 v[142:145], v96 offset:19072
	v_add_f32_dpp v0, v0, v0 row_ror:2 row_mask:0xf bank_mask:0xf bound_ctrl:1
	ds_read_b128 v[138:141], v96 offset:18816
	ds_read_b128 v[146:149], v96 offset:19328
	ds_read_b128 v[182:185], v96 offset:19840
	v_add_f32_dpp v0, v0, v0 row_ror:1 row_mask:0xf bank_mask:0xf bound_ctrl:1
	v_pk_fma_f32 v[86:87], v[0:1], v[202:203], v[206:207] op_sel_hi:[0,1,1]
	v_pk_fma_f32 v[84:85], v[0:1], v[204:205], v[208:209] op_sel_hi:[0,1,1]
	v_pk_mul_f32 v[88:89], v[86:87], v[14:15]
	v_pk_fma_f32 v[22:23], v[86:87], v[10:11], v[22:23]
	v_pk_fma_f32 v[88:89], v[84:85], v[16:17], v[88:89]
	v_pk_mul_f32 v[186:187], v[86:87], v[210:211]
	v_add_f32_e32 v0, v88, v89
	v_pk_fma_f32 v[24:25], v[84:85], v[12:13], v[24:25]
	v_pk_fma_f32 v[186:187], v[84:85], v[212:213], v[186:187]
	v_add_f32_dpp v0, v0, v0 row_ror:8 row_mask:0xf bank_mask:0xf bound_ctrl:1
	s_waitcnt lgkmcnt(6)
	v_pk_mul_f32 v[124:125], v[124:125], v[154:155] op_sel_hi:[1,0]
	v_add_f32_e32 v219, v186, v187
	v_add_f32_dpp v0, v0, v0 row_ror:4 row_mask:0xf bank_mask:0xf bound_ctrl:1
	v_pk_mul_f32 v[126:127], v[126:127], v[154:155] op_sel_hi:[1,0]
	ds_write2st64_b32 v98, v218, v219 offset0:40 offset1:44
	ds_read_b128 v[206:209], v96 offset:20928
	ds_read_b32 v216, v97 offset:20160
	ds_read_b128 v[198:201], v96 offset:20416
	v_add_f32_dpp v0, v0, v0 row_ror:2 row_mask:0xf bank_mask:0xf bound_ctrl:1
	ds_read_b128 v[194:197], v96 offset:20160
	ds_read_b128 v[202:205], v96 offset:20672
	ds_read_b128 v[210:213], v96 offset:21184
	v_add_f32_dpp v0, v0, v0 row_ror:1 row_mask:0xf bank_mask:0xf bound_ctrl:1
	v_pk_fma_f32 v[86:87], v[0:1], v[18:19], v[22:23] op_sel_hi:[0,1,1]
	v_pk_fma_f32 v[84:85], v[0:1], v[20:21], v[24:25] op_sel_hi:[0,1,1]
	v_pk_mul_f32 v[88:89], v[86:87], v[116:117]
	v_pk_fma_f32 v[124:125], v[86:87], v[112:113], v[124:125]
	v_pk_fma_f32 v[88:89], v[84:85], v[118:119], v[88:89]
	v_pk_mul_f32 v[186:187], v[86:87], v[108:109]
	v_add_f32_e32 v0, v88, v89
	v_pk_fma_f32 v[126:127], v[84:85], v[114:115], v[126:127]
	v_pk_fma_f32 v[186:187], v[84:85], v[110:111], v[186:187]
	v_add_f32_dpp v0, v0, v0 row_ror:8 row_mask:0xf bank_mask:0xf bound_ctrl:1
	s_waitcnt lgkmcnt(7)
	v_pk_mul_f32 v[150:151], v[150:151], v[214:215] op_sel_hi:[1,0]
	v_add_f32_e32 v218, v186, v187
	v_add_f32_dpp v0, v0, v0 row_ror:4 row_mask:0xf bank_mask:0xf bound_ctrl:1
	v_pk_mul_f32 v[152:153], v[152:153], v[214:215] op_sel_hi:[1,0]
	ds_read_b128 v[22:25], v96 offset:22272
	ds_read_b32 v128, v97 offset:21504
	ds_read_b128 v[14:17], v96 offset:21760
	v_add_f32_dpp v0, v0, v0 row_ror:2 row_mask:0xf bank_mask:0xf bound_ctrl:1
	ds_read_b128 v[10:13], v96 offset:21504
	ds_read_b128 v[18:21], v96 offset:22016
	ds_read_b128 v[108:111], v96 offset:22528
	v_add_f32_dpp v0, v0, v0 row_ror:1 row_mask:0xf bank_mask:0xf bound_ctrl:1
	v_pk_fma_f32 v[86:87], v[0:1], v[120:121], v[124:125] op_sel_hi:[0,1,1]
	v_pk_fma_f32 v[84:85], v[0:1], v[122:123], v[126:127] op_sel_hi:[0,1,1]
	v_pk_mul_f32 v[88:89], v[86:87], v[142:143]
	v_pk_fma_f32 v[150:151], v[86:87], v[138:139], v[150:151]
	v_pk_fma_f32 v[88:89], v[84:85], v[144:145], v[88:89]
	v_pk_mul_f32 v[186:187], v[86:87], v[134:135]
	v_add_f32_e32 v0, v88, v89
	v_pk_fma_f32 v[152:153], v[84:85], v[140:141], v[152:153]
	v_pk_fma_f32 v[186:187], v[84:85], v[136:137], v[186:187]
	v_add_f32_dpp v0, v0, v0 row_ror:8 row_mask:0xf bank_mask:0xf bound_ctrl:1
	s_waitcnt lgkmcnt(6)
	v_pk_mul_f32 v[206:207], v[206:207], v[216:217] op_sel_hi:[1,0]
	v_add_f32_e32 v219, v186, v187
	v_add_f32_dpp v0, v0, v0 row_ror:4 row_mask:0xf bank_mask:0xf bound_ctrl:1
	v_pk_mul_f32 v[208:209], v[208:209], v[216:217] op_sel_hi:[1,0]
	ds_write2st64_b32 v98, v218, v219 offset0:48 offset1:52
	ds_read_b128 v[124:127], v96 offset:23616
	ds_read_b32 v154, v97 offset:22848
	ds_read_b128 v[116:119], v96 offset:23104
	v_add_f32_dpp v0, v0, v0 row_ror:2 row_mask:0xf bank_mask:0xf bound_ctrl:1
	ds_read_b128 v[112:115], v96 offset:22848
	ds_read_b128 v[120:123], v96 offset:23360
	ds_read_b128 v[134:137], v96 offset:23872
	v_add_f32_dpp v0, v0, v0 row_ror:1 row_mask:0xf bank_mask:0xf bound_ctrl:1
	v_pk_fma_f32 v[86:87], v[0:1], v[146:147], v[150:151] op_sel_hi:[0,1,1]
	v_pk_fma_f32 v[84:85], v[0:1], v[148:149], v[152:153] op_sel_hi:[0,1,1]
	v_pk_mul_f32 v[88:89], v[86:87], v[198:199]
	v_pk_fma_f32 v[206:207], v[86:87], v[194:195], v[206:207]
	v_pk_fma_f32 v[88:89], v[84:85], v[200:201], v[88:89]
	v_pk_mul_f32 v[186:187], v[86:87], v[182:183]
	v_add_f32_e32 v0, v88, v89
	v_pk_fma_f32 v[208:209], v[84:85], v[196:197], v[208:209]
	v_pk_fma_f32 v[186:187], v[84:85], v[184:185], v[186:187]
	v_add_f32_dpp v0, v0, v0 row_ror:8 row_mask:0xf bank_mask:0xf bound_ctrl:1
	s_waitcnt lgkmcnt(7)
	v_pk_mul_f32 v[22:23], v[22:23], v[128:129] op_sel_hi:[1,0]
	v_add_f32_e32 v218, v186, v187
	v_add_f32_dpp v0, v0, v0 row_ror:4 row_mask:0xf bank_mask:0xf bound_ctrl:1
	v_pk_mul_f32 v[24:25], v[24:25], v[128:129] op_sel_hi:[1,0]
	ds_read_b128 v[150:153], v96 offset:24960
	ds_read_b32 v214, v97 offset:24192
	ds_read_b128 v[142:145], v96 offset:24448
	v_add_f32_dpp v0, v0, v0 row_ror:2 row_mask:0xf bank_mask:0xf bound_ctrl:1
	ds_read_b128 v[138:141], v96 offset:24192
	ds_read_b128 v[146:149], v96 offset:24704
	ds_read_b128 v[182:185], v96 offset:25216
	v_add_f32_dpp v0, v0, v0 row_ror:1 row_mask:0xf bank_mask:0xf bound_ctrl:1
	v_pk_fma_f32 v[86:87], v[0:1], v[202:203], v[206:207] op_sel_hi:[0,1,1]
	v_pk_fma_f32 v[84:85], v[0:1], v[204:205], v[208:209] op_sel_hi:[0,1,1]
	v_pk_mul_f32 v[88:89], v[86:87], v[14:15]
	v_pk_fma_f32 v[22:23], v[86:87], v[10:11], v[22:23]
	v_pk_fma_f32 v[88:89], v[84:85], v[16:17], v[88:89]
	v_pk_mul_f32 v[186:187], v[86:87], v[210:211]
	v_add_f32_e32 v0, v88, v89
	v_pk_fma_f32 v[24:25], v[84:85], v[12:13], v[24:25]
	v_pk_fma_f32 v[186:187], v[84:85], v[212:213], v[186:187]
	v_add_f32_dpp v0, v0, v0 row_ror:8 row_mask:0xf bank_mask:0xf bound_ctrl:1
	s_waitcnt lgkmcnt(6)
	v_pk_mul_f32 v[124:125], v[124:125], v[154:155] op_sel_hi:[1,0]
	v_add_f32_e32 v219, v186, v187
	v_add_f32_dpp v0, v0, v0 row_ror:4 row_mask:0xf bank_mask:0xf bound_ctrl:1
	v_pk_mul_f32 v[126:127], v[126:127], v[154:155] op_sel_hi:[1,0]
	ds_write2st64_b32 v98, v218, v219 offset0:56 offset1:60
	ds_read_b128 v[206:209], v96 offset:26304
	ds_read_b32 v216, v97 offset:25536
	ds_read_b128 v[198:201], v96 offset:25792
	v_add_f32_dpp v0, v0, v0 row_ror:2 row_mask:0xf bank_mask:0xf bound_ctrl:1
	ds_read_b128 v[194:197], v96 offset:25536
	ds_read_b128 v[202:205], v96 offset:26048
	ds_read_b128 v[210:213], v96 offset:26560
	v_add_f32_dpp v0, v0, v0 row_ror:1 row_mask:0xf bank_mask:0xf bound_ctrl:1
	v_pk_fma_f32 v[86:87], v[0:1], v[18:19], v[22:23] op_sel_hi:[0,1,1]
	v_pk_fma_f32 v[84:85], v[0:1], v[20:21], v[24:25] op_sel_hi:[0,1,1]
	v_pk_mul_f32 v[88:89], v[86:87], v[116:117]
	v_pk_fma_f32 v[124:125], v[86:87], v[112:113], v[124:125]
	v_pk_fma_f32 v[88:89], v[84:85], v[118:119], v[88:89]
	v_pk_mul_f32 v[186:187], v[86:87], v[108:109]
	v_add_f32_e32 v0, v88, v89
	v_pk_fma_f32 v[126:127], v[84:85], v[114:115], v[126:127]
	v_pk_fma_f32 v[186:187], v[84:85], v[110:111], v[186:187]
	v_add_f32_dpp v0, v0, v0 row_ror:8 row_mask:0xf bank_mask:0xf bound_ctrl:1
	s_waitcnt lgkmcnt(7)
	v_pk_mul_f32 v[150:151], v[150:151], v[214:215] op_sel_hi:[1,0]
	v_add_f32_e32 v218, v186, v187
	v_add_f32_dpp v0, v0, v0 row_ror:4 row_mask:0xf bank_mask:0xf bound_ctrl:1
	v_pk_mul_f32 v[152:153], v[152:153], v[214:215] op_sel_hi:[1,0]
	ds_read_b128 v[22:25], v96 offset:27648
	ds_read_b32 v128, v97 offset:26880
	ds_read_b128 v[14:17], v96 offset:27136
	v_add_f32_dpp v0, v0, v0 row_ror:2 row_mask:0xf bank_mask:0xf bound_ctrl:1
	ds_read_b128 v[10:13], v96 offset:26880
	ds_read_b128 v[18:21], v96 offset:27392
	ds_read_b128 v[108:111], v96 offset:27904
	v_add_f32_dpp v0, v0, v0 row_ror:1 row_mask:0xf bank_mask:0xf bound_ctrl:1
	v_pk_fma_f32 v[86:87], v[0:1], v[120:121], v[124:125] op_sel_hi:[0,1,1]
	v_pk_fma_f32 v[84:85], v[0:1], v[122:123], v[126:127] op_sel_hi:[0,1,1]
	v_pk_mul_f32 v[88:89], v[86:87], v[142:143]
	v_pk_fma_f32 v[150:151], v[86:87], v[138:139], v[150:151]
	v_pk_fma_f32 v[88:89], v[84:85], v[144:145], v[88:89]
	v_pk_mul_f32 v[186:187], v[86:87], v[134:135]
	v_add_f32_e32 v0, v88, v89
	v_pk_fma_f32 v[152:153], v[84:85], v[140:141], v[152:153]
	v_pk_fma_f32 v[186:187], v[84:85], v[136:137], v[186:187]
	v_add_f32_dpp v0, v0, v0 row_ror:8 row_mask:0xf bank_mask:0xf bound_ctrl:1
	s_waitcnt lgkmcnt(6)
	v_pk_mul_f32 v[206:207], v[206:207], v[216:217] op_sel_hi:[1,0]
	v_add_f32_e32 v219, v186, v187
	v_add_f32_dpp v0, v0, v0 row_ror:4 row_mask:0xf bank_mask:0xf bound_ctrl:1
	v_pk_mul_f32 v[208:209], v[208:209], v[216:217] op_sel_hi:[1,0]
	ds_write2st64_b32 v98, v218, v219 offset0:64 offset1:68
	ds_read_b128 v[124:127], v96 offset:28992
	ds_read_b32 v154, v97 offset:28224
	ds_read_b128 v[116:119], v96 offset:28480
	v_add_f32_dpp v0, v0, v0 row_ror:2 row_mask:0xf bank_mask:0xf bound_ctrl:1
	ds_read_b128 v[112:115], v96 offset:28224
	ds_read_b128 v[120:123], v96 offset:28736
	ds_read_b128 v[134:137], v96 offset:29248
	v_add_f32_dpp v0, v0, v0 row_ror:1 row_mask:0xf bank_mask:0xf bound_ctrl:1
	v_pk_fma_f32 v[86:87], v[0:1], v[146:147], v[150:151] op_sel_hi:[0,1,1]
	v_pk_fma_f32 v[84:85], v[0:1], v[148:149], v[152:153] op_sel_hi:[0,1,1]
	v_pk_mul_f32 v[88:89], v[86:87], v[198:199]
	v_pk_fma_f32 v[206:207], v[86:87], v[194:195], v[206:207]
	v_pk_fma_f32 v[88:89], v[84:85], v[200:201], v[88:89]
	v_pk_mul_f32 v[186:187], v[86:87], v[182:183]
	v_add_f32_e32 v0, v88, v89
	v_pk_fma_f32 v[208:209], v[84:85], v[196:197], v[208:209]
	v_pk_fma_f32 v[186:187], v[84:85], v[184:185], v[186:187]
	v_add_f32_dpp v0, v0, v0 row_ror:8 row_mask:0xf bank_mask:0xf bound_ctrl:1
	s_waitcnt lgkmcnt(7)
	v_pk_mul_f32 v[22:23], v[22:23], v[128:129] op_sel_hi:[1,0]
	v_add_f32_e32 v218, v186, v187
	v_add_f32_dpp v0, v0, v0 row_ror:4 row_mask:0xf bank_mask:0xf bound_ctrl:1
	v_pk_mul_f32 v[24:25], v[24:25], v[128:129] op_sel_hi:[1,0]
	ds_read_b128 v[150:153], v96 offset:30336
	ds_read_b32 v214, v97 offset:29568
	ds_read_b128 v[142:145], v96 offset:29824
	v_add_f32_dpp v0, v0, v0 row_ror:2 row_mask:0xf bank_mask:0xf bound_ctrl:1
	ds_read_b128 v[138:141], v96 offset:29568
	ds_read_b128 v[146:149], v96 offset:30080
	ds_read_b128 v[182:185], v96 offset:30592
	v_add_f32_dpp v0, v0, v0 row_ror:1 row_mask:0xf bank_mask:0xf bound_ctrl:1
	v_pk_fma_f32 v[86:87], v[0:1], v[202:203], v[206:207] op_sel_hi:[0,1,1]
	v_pk_fma_f32 v[84:85], v[0:1], v[204:205], v[208:209] op_sel_hi:[0,1,1]
	v_pk_mul_f32 v[88:89], v[86:87], v[14:15]
	v_pk_fma_f32 v[22:23], v[86:87], v[10:11], v[22:23]
	v_pk_fma_f32 v[88:89], v[84:85], v[16:17], v[88:89]
	v_pk_mul_f32 v[186:187], v[86:87], v[210:211]
	v_add_f32_e32 v0, v88, v89
	v_pk_fma_f32 v[24:25], v[84:85], v[12:13], v[24:25]
	v_pk_fma_f32 v[186:187], v[84:85], v[212:213], v[186:187]
	v_add_f32_dpp v0, v0, v0 row_ror:8 row_mask:0xf bank_mask:0xf bound_ctrl:1
	s_waitcnt lgkmcnt(6)
	v_pk_mul_f32 v[124:125], v[124:125], v[154:155] op_sel_hi:[1,0]
	v_add_f32_e32 v219, v186, v187
	v_add_f32_dpp v0, v0, v0 row_ror:4 row_mask:0xf bank_mask:0xf bound_ctrl:1
	v_pk_mul_f32 v[126:127], v[126:127], v[154:155] op_sel_hi:[1,0]
	ds_write2st64_b32 v98, v218, v219 offset0:72 offset1:76
	ds_read_b128 v[206:209], v96 offset:31680
	ds_read_b32 v216, v97 offset:30912
	ds_read_b128 v[198:201], v96 offset:31168
	v_add_f32_dpp v0, v0, v0 row_ror:2 row_mask:0xf bank_mask:0xf bound_ctrl:1
	ds_read_b128 v[194:197], v96 offset:30912
	ds_read_b128 v[202:205], v96 offset:31424
	ds_read_b128 v[210:213], v96 offset:31936
	v_add_f32_dpp v0, v0, v0 row_ror:1 row_mask:0xf bank_mask:0xf bound_ctrl:1
	v_pk_fma_f32 v[86:87], v[0:1], v[18:19], v[22:23] op_sel_hi:[0,1,1]
	v_pk_fma_f32 v[84:85], v[0:1], v[20:21], v[24:25] op_sel_hi:[0,1,1]
	v_pk_mul_f32 v[88:89], v[86:87], v[116:117]
	v_pk_fma_f32 v[124:125], v[86:87], v[112:113], v[124:125]
	v_pk_fma_f32 v[88:89], v[84:85], v[118:119], v[88:89]
	v_pk_mul_f32 v[186:187], v[86:87], v[108:109]
	v_add_f32_e32 v0, v88, v89
	v_pk_fma_f32 v[126:127], v[84:85], v[114:115], v[126:127]
	v_pk_fma_f32 v[186:187], v[84:85], v[110:111], v[186:187]
	v_add_f32_dpp v0, v0, v0 row_ror:8 row_mask:0xf bank_mask:0xf bound_ctrl:1
	s_waitcnt lgkmcnt(7)
	v_pk_mul_f32 v[150:151], v[150:151], v[214:215] op_sel_hi:[1,0]
	v_add_f32_e32 v218, v186, v187
	v_add_f32_dpp v0, v0, v0 row_ror:4 row_mask:0xf bank_mask:0xf bound_ctrl:1
	v_pk_mul_f32 v[152:153], v[152:153], v[214:215] op_sel_hi:[1,0]
	ds_read_b128 v[22:25], v96 offset:33024
	ds_read_b32 v128, v97 offset:32256
	ds_read_b128 v[14:17], v96 offset:32512
	v_add_f32_dpp v0, v0, v0 row_ror:2 row_mask:0xf bank_mask:0xf bound_ctrl:1
	ds_read_b128 v[10:13], v96 offset:32256
	ds_read_b128 v[18:21], v96 offset:32768
	ds_read_b128 v[108:111], v96 offset:33280
	v_add_f32_dpp v0, v0, v0 row_ror:1 row_mask:0xf bank_mask:0xf bound_ctrl:1
	v_pk_fma_f32 v[86:87], v[0:1], v[120:121], v[124:125] op_sel_hi:[0,1,1]
	v_pk_fma_f32 v[84:85], v[0:1], v[122:123], v[126:127] op_sel_hi:[0,1,1]
	v_pk_mul_f32 v[88:89], v[86:87], v[142:143]
	v_pk_fma_f32 v[150:151], v[86:87], v[138:139], v[150:151]
	v_pk_fma_f32 v[88:89], v[84:85], v[144:145], v[88:89]
	v_pk_mul_f32 v[186:187], v[86:87], v[134:135]
	v_add_f32_e32 v0, v88, v89
	v_pk_fma_f32 v[152:153], v[84:85], v[140:141], v[152:153]
	v_pk_fma_f32 v[186:187], v[84:85], v[136:137], v[186:187]
	v_add_f32_dpp v0, v0, v0 row_ror:8 row_mask:0xf bank_mask:0xf bound_ctrl:1
	s_waitcnt lgkmcnt(6)
	v_pk_mul_f32 v[206:207], v[206:207], v[216:217] op_sel_hi:[1,0]
	v_add_f32_e32 v219, v186, v187
	v_add_f32_dpp v0, v0, v0 row_ror:4 row_mask:0xf bank_mask:0xf bound_ctrl:1
	v_pk_mul_f32 v[208:209], v[208:209], v[216:217] op_sel_hi:[1,0]
	ds_write2st64_b32 v98, v218, v219 offset0:80 offset1:84
	ds_read_b128 v[124:127], v96 offset:34368
	ds_read_b32 v154, v97 offset:33600
	ds_read_b128 v[116:119], v96 offset:33856
	v_add_f32_dpp v0, v0, v0 row_ror:2 row_mask:0xf bank_mask:0xf bound_ctrl:1
	ds_read_b128 v[112:115], v96 offset:33600
	ds_read_b128 v[120:123], v96 offset:34112
	ds_read_b128 v[134:137], v96 offset:34624
	v_add_f32_dpp v0, v0, v0 row_ror:1 row_mask:0xf bank_mask:0xf bound_ctrl:1
	v_pk_fma_f32 v[86:87], v[0:1], v[146:147], v[150:151] op_sel_hi:[0,1,1]
	v_pk_fma_f32 v[84:85], v[0:1], v[148:149], v[152:153] op_sel_hi:[0,1,1]
	v_pk_mul_f32 v[88:89], v[86:87], v[198:199]
	v_pk_fma_f32 v[206:207], v[86:87], v[194:195], v[206:207]
	v_pk_fma_f32 v[88:89], v[84:85], v[200:201], v[88:89]
	v_pk_mul_f32 v[186:187], v[86:87], v[182:183]
	v_add_f32_e32 v0, v88, v89
	v_pk_fma_f32 v[208:209], v[84:85], v[196:197], v[208:209]
	v_pk_fma_f32 v[186:187], v[84:85], v[184:185], v[186:187]
	v_add_f32_dpp v0, v0, v0 row_ror:8 row_mask:0xf bank_mask:0xf bound_ctrl:1
	s_waitcnt lgkmcnt(7)
	v_pk_mul_f32 v[22:23], v[22:23], v[128:129] op_sel_hi:[1,0]
	v_add_f32_e32 v218, v186, v187
	v_add_f32_dpp v0, v0, v0 row_ror:4 row_mask:0xf bank_mask:0xf bound_ctrl:1
	v_pk_mul_f32 v[24:25], v[24:25], v[128:129] op_sel_hi:[1,0]
	ds_read_b128 v[150:153], v96 offset:35712
	ds_read_b32 v214, v97 offset:34944
	ds_read_b128 v[142:145], v96 offset:35200
	v_add_f32_dpp v0, v0, v0 row_ror:2 row_mask:0xf bank_mask:0xf bound_ctrl:1
	ds_read_b128 v[138:141], v96 offset:34944
	ds_read_b128 v[146:149], v96 offset:35456
	ds_read_b128 v[182:185], v96 offset:35968
	v_add_f32_dpp v0, v0, v0 row_ror:1 row_mask:0xf bank_mask:0xf bound_ctrl:1
	v_pk_fma_f32 v[86:87], v[0:1], v[202:203], v[206:207] op_sel_hi:[0,1,1]
	v_pk_fma_f32 v[84:85], v[0:1], v[204:205], v[208:209] op_sel_hi:[0,1,1]
	v_pk_mul_f32 v[88:89], v[86:87], v[14:15]
	v_pk_fma_f32 v[22:23], v[86:87], v[10:11], v[22:23]
	v_pk_fma_f32 v[88:89], v[84:85], v[16:17], v[88:89]
	v_pk_mul_f32 v[186:187], v[86:87], v[210:211]
	v_add_f32_e32 v0, v88, v89
	v_pk_fma_f32 v[24:25], v[84:85], v[12:13], v[24:25]
	v_pk_fma_f32 v[186:187], v[84:85], v[212:213], v[186:187]
	v_add_f32_dpp v0, v0, v0 row_ror:8 row_mask:0xf bank_mask:0xf bound_ctrl:1
	s_waitcnt lgkmcnt(6)
	v_pk_mul_f32 v[124:125], v[124:125], v[154:155] op_sel_hi:[1,0]
	v_add_f32_e32 v219, v186, v187
	v_add_f32_dpp v0, v0, v0 row_ror:4 row_mask:0xf bank_mask:0xf bound_ctrl:1
	v_pk_mul_f32 v[126:127], v[126:127], v[154:155] op_sel_hi:[1,0]
	ds_write2st64_b32 v98, v218, v219 offset0:88 offset1:92
	ds_read_b128 v[206:209], v96 offset:37056
	ds_read_b32 v216, v97 offset:36288
	ds_read_b128 v[198:201], v96 offset:36544
	v_add_f32_dpp v0, v0, v0 row_ror:2 row_mask:0xf bank_mask:0xf bound_ctrl:1
	ds_read_b128 v[194:197], v96 offset:36288
	ds_read_b128 v[202:205], v96 offset:36800
	ds_read_b128 v[210:213], v96 offset:37312
	v_add_f32_dpp v0, v0, v0 row_ror:1 row_mask:0xf bank_mask:0xf bound_ctrl:1
	v_pk_fma_f32 v[86:87], v[0:1], v[18:19], v[22:23] op_sel_hi:[0,1,1]
	v_pk_fma_f32 v[84:85], v[0:1], v[20:21], v[24:25] op_sel_hi:[0,1,1]
	v_pk_mul_f32 v[88:89], v[86:87], v[116:117]
	v_pk_fma_f32 v[124:125], v[86:87], v[112:113], v[124:125]
	v_pk_fma_f32 v[88:89], v[84:85], v[118:119], v[88:89]
	v_pk_mul_f32 v[186:187], v[86:87], v[108:109]
	v_add_f32_e32 v0, v88, v89
	v_pk_fma_f32 v[126:127], v[84:85], v[114:115], v[126:127]
	v_pk_fma_f32 v[186:187], v[84:85], v[110:111], v[186:187]
	v_add_f32_dpp v0, v0, v0 row_ror:8 row_mask:0xf bank_mask:0xf bound_ctrl:1
	s_waitcnt lgkmcnt(7)
	v_pk_mul_f32 v[150:151], v[150:151], v[214:215] op_sel_hi:[1,0]
	v_add_f32_e32 v218, v186, v187
	v_add_f32_dpp v0, v0, v0 row_ror:4 row_mask:0xf bank_mask:0xf bound_ctrl:1
	v_pk_mul_f32 v[152:153], v[152:153], v[214:215] op_sel_hi:[1,0]
	ds_read_b128 v[22:25], v96 offset:38400
	ds_read_b32 v128, v97 offset:37632
	ds_read_b128 v[14:17], v96 offset:37888
	v_add_f32_dpp v0, v0, v0 row_ror:2 row_mask:0xf bank_mask:0xf bound_ctrl:1
	ds_read_b128 v[10:13], v96 offset:37632
	ds_read_b128 v[18:21], v96 offset:38144
	ds_read_b128 v[108:111], v96 offset:38656
	v_add_f32_dpp v0, v0, v0 row_ror:1 row_mask:0xf bank_mask:0xf bound_ctrl:1
	v_pk_fma_f32 v[86:87], v[0:1], v[120:121], v[124:125] op_sel_hi:[0,1,1]
	v_pk_fma_f32 v[84:85], v[0:1], v[122:123], v[126:127] op_sel_hi:[0,1,1]
	v_pk_mul_f32 v[88:89], v[86:87], v[142:143]
	v_pk_fma_f32 v[150:151], v[86:87], v[138:139], v[150:151]
	v_pk_fma_f32 v[88:89], v[84:85], v[144:145], v[88:89]
	v_pk_mul_f32 v[186:187], v[86:87], v[134:135]
	v_add_f32_e32 v0, v88, v89
	v_pk_fma_f32 v[152:153], v[84:85], v[140:141], v[152:153]
	v_pk_fma_f32 v[186:187], v[84:85], v[136:137], v[186:187]
	v_add_f32_dpp v0, v0, v0 row_ror:8 row_mask:0xf bank_mask:0xf bound_ctrl:1
	s_waitcnt lgkmcnt(6)
	v_pk_mul_f32 v[206:207], v[206:207], v[216:217] op_sel_hi:[1,0]
	v_add_f32_e32 v219, v186, v187
	v_add_f32_dpp v0, v0, v0 row_ror:4 row_mask:0xf bank_mask:0xf bound_ctrl:1
	v_pk_mul_f32 v[208:209], v[208:209], v[216:217] op_sel_hi:[1,0]
	ds_write2st64_b32 v98, v218, v219 offset0:96 offset1:100
	ds_read_b128 v[124:127], v96 offset:39744
	ds_read_b32 v154, v97 offset:38976
	ds_read_b128 v[116:119], v96 offset:39232
	v_add_f32_dpp v0, v0, v0 row_ror:2 row_mask:0xf bank_mask:0xf bound_ctrl:1
	ds_read_b128 v[112:115], v96 offset:38976
	ds_read_b128 v[120:123], v96 offset:39488
	ds_read_b128 v[134:137], v96 offset:40000
	v_add_f32_dpp v0, v0, v0 row_ror:1 row_mask:0xf bank_mask:0xf bound_ctrl:1
	v_pk_fma_f32 v[86:87], v[0:1], v[146:147], v[150:151] op_sel_hi:[0,1,1]
	v_pk_fma_f32 v[84:85], v[0:1], v[148:149], v[152:153] op_sel_hi:[0,1,1]
	v_pk_mul_f32 v[88:89], v[86:87], v[198:199]
	v_pk_fma_f32 v[206:207], v[86:87], v[194:195], v[206:207]
	v_pk_fma_f32 v[88:89], v[84:85], v[200:201], v[88:89]
	v_pk_mul_f32 v[186:187], v[86:87], v[182:183]
	v_add_f32_e32 v0, v88, v89
	v_pk_fma_f32 v[208:209], v[84:85], v[196:197], v[208:209]
	v_pk_fma_f32 v[186:187], v[84:85], v[184:185], v[186:187]
	v_add_f32_dpp v0, v0, v0 row_ror:8 row_mask:0xf bank_mask:0xf bound_ctrl:1
	s_waitcnt lgkmcnt(7)
	v_pk_mul_f32 v[22:23], v[22:23], v[128:129] op_sel_hi:[1,0]
	v_add_f32_e32 v218, v186, v187
	v_add_f32_dpp v0, v0, v0 row_ror:4 row_mask:0xf bank_mask:0xf bound_ctrl:1
	v_pk_mul_f32 v[24:25], v[24:25], v[128:129] op_sel_hi:[1,0]
	ds_read_b128 v[150:153], v96 offset:41088
	ds_read_b32 v214, v97 offset:40320
	ds_read_b128 v[142:145], v96 offset:40576
	v_add_f32_dpp v0, v0, v0 row_ror:2 row_mask:0xf bank_mask:0xf bound_ctrl:1
	ds_read_b128 v[138:141], v96 offset:40320
	ds_read_b128 v[146:149], v96 offset:40832
	ds_read_b128 v[182:185], v96 offset:41344
	v_add_f32_dpp v0, v0, v0 row_ror:1 row_mask:0xf bank_mask:0xf bound_ctrl:1
	v_pk_fma_f32 v[86:87], v[0:1], v[202:203], v[206:207] op_sel_hi:[0,1,1]
	v_pk_fma_f32 v[84:85], v[0:1], v[204:205], v[208:209] op_sel_hi:[0,1,1]
	v_pk_mul_f32 v[88:89], v[86:87], v[14:15]
	v_pk_fma_f32 v[22:23], v[86:87], v[10:11], v[22:23]
	v_pk_fma_f32 v[88:89], v[84:85], v[16:17], v[88:89]
	v_pk_mul_f32 v[186:187], v[86:87], v[210:211]
	v_add_f32_e32 v0, v88, v89
	v_pk_fma_f32 v[24:25], v[84:85], v[12:13], v[24:25]
	v_pk_fma_f32 v[186:187], v[84:85], v[212:213], v[186:187]
	v_add_f32_dpp v0, v0, v0 row_ror:8 row_mask:0xf bank_mask:0xf bound_ctrl:1
	s_waitcnt lgkmcnt(6)
	v_pk_mul_f32 v[124:125], v[124:125], v[154:155] op_sel_hi:[1,0]
	v_add_f32_e32 v219, v186, v187
	v_add_f32_dpp v0, v0, v0 row_ror:4 row_mask:0xf bank_mask:0xf bound_ctrl:1
	v_pk_mul_f32 v[126:127], v[126:127], v[154:155] op_sel_hi:[1,0]
	ds_write2st64_b32 v98, v218, v219 offset0:104 offset1:108
	ds_read_b128 v[206:209], v96 offset:42432
	ds_read_b32 v216, v97 offset:41664
	ds_read_b128 v[198:201], v96 offset:41920
	v_add_f32_dpp v0, v0, v0 row_ror:2 row_mask:0xf bank_mask:0xf bound_ctrl:1
	ds_read_b128 v[194:197], v96 offset:41664
	ds_read_b128 v[202:205], v96 offset:42176
	ds_read_b128 v[210:213], v96 offset:42688
	v_add_f32_dpp v0, v0, v0 row_ror:1 row_mask:0xf bank_mask:0xf bound_ctrl:1
	v_pk_fma_f32 v[86:87], v[0:1], v[18:19], v[22:23] op_sel_hi:[0,1,1]
	v_pk_fma_f32 v[84:85], v[0:1], v[20:21], v[24:25] op_sel_hi:[0,1,1]
	v_pk_mul_f32 v[88:89], v[86:87], v[116:117]
	v_pk_fma_f32 v[124:125], v[86:87], v[112:113], v[124:125]
	v_pk_fma_f32 v[88:89], v[84:85], v[118:119], v[88:89]
	v_pk_mul_f32 v[186:187], v[86:87], v[108:109]
	v_add_f32_e32 v0, v88, v89
	v_pk_fma_f32 v[126:127], v[84:85], v[114:115], v[126:127]
	v_pk_fma_f32 v[186:187], v[84:85], v[110:111], v[186:187]
	v_add_f32_dpp v0, v0, v0 row_ror:8 row_mask:0xf bank_mask:0xf bound_ctrl:1
	s_waitcnt lgkmcnt(7)
	v_pk_mul_f32 v[150:151], v[150:151], v[214:215] op_sel_hi:[1,0]
	v_add_f32_e32 v218, v186, v187
	v_add_f32_dpp v0, v0, v0 row_ror:4 row_mask:0xf bank_mask:0xf bound_ctrl:1
	v_pk_mul_f32 v[152:153], v[152:153], v[214:215] op_sel_hi:[1,0]
	s_nop 0
	v_add_f32_dpp v0, v0, v0 row_ror:2 row_mask:0xf bank_mask:0xf bound_ctrl:1
	s_nop 1
	v_add_f32_dpp v0, v0, v0 row_ror:1 row_mask:0xf bank_mask:0xf bound_ctrl:1
	v_pk_fma_f32 v[86:87], v[0:1], v[120:121], v[124:125] op_sel_hi:[0,1,1]
	v_pk_fma_f32 v[84:85], v[0:1], v[122:123], v[126:127] op_sel_hi:[0,1,1]
	v_pk_mul_f32 v[88:89], v[86:87], v[142:143]
	v_pk_fma_f32 v[150:151], v[86:87], v[138:139], v[150:151]
	v_pk_fma_f32 v[88:89], v[84:85], v[144:145], v[88:89]
	v_pk_mul_f32 v[186:187], v[86:87], v[134:135]
	v_add_f32_e32 v0, v88, v89
	v_pk_fma_f32 v[152:153], v[84:85], v[140:141], v[152:153]
	v_pk_fma_f32 v[186:187], v[84:85], v[136:137], v[186:187]
	v_add_f32_dpp v0, v0, v0 row_ror:8 row_mask:0xf bank_mask:0xf bound_ctrl:1
	s_waitcnt lgkmcnt(0)
	v_pk_mul_f32 v[206:207], v[206:207], v[216:217] op_sel_hi:[1,0]
	v_add_f32_e32 v219, v186, v187
	v_add_f32_dpp v0, v0, v0 row_ror:4 row_mask:0xf bank_mask:0xf bound_ctrl:1
	v_pk_mul_f32 v[208:209], v[208:209], v[216:217] op_sel_hi:[1,0]
	ds_write2st64_b32 v98, v218, v219 offset0:112 offset1:116
	v_add_f32_dpp v0, v0, v0 row_ror:2 row_mask:0xf bank_mask:0xf bound_ctrl:1
	s_nop 1
	v_add_f32_dpp v0, v0, v0 row_ror:1 row_mask:0xf bank_mask:0xf bound_ctrl:1
	v_pk_fma_f32 v[86:87], v[0:1], v[146:147], v[150:151] op_sel_hi:[0,1,1]
	v_pk_fma_f32 v[84:85], v[0:1], v[148:149], v[152:153] op_sel_hi:[0,1,1]
	v_pk_mul_f32 v[88:89], v[86:87], v[198:199]
	v_pk_fma_f32 v[206:207], v[86:87], v[194:195], v[206:207]
	v_pk_fma_f32 v[88:89], v[84:85], v[200:201], v[88:89]
	v_pk_mul_f32 v[186:187], v[86:87], v[182:183]
	v_add_f32_e32 v0, v88, v89
	v_pk_fma_f32 v[208:209], v[84:85], v[196:197], v[208:209]
	v_pk_fma_f32 v[186:187], v[84:85], v[184:185], v[186:187]
	v_add_f32_dpp v0, v0, v0 row_ror:8 row_mask:0xf bank_mask:0xf bound_ctrl:1
	v_add_f32_e32 v218, v186, v187
	s_nop 0
	v_add_f32_dpp v0, v0, v0 row_ror:4 row_mask:0xf bank_mask:0xf bound_ctrl:1
	s_nop 1
	v_add_f32_dpp v0, v0, v0 row_ror:2 row_mask:0xf bank_mask:0xf bound_ctrl:1
	s_nop 1
	v_add_f32_dpp v0, v0, v0 row_ror:1 row_mask:0xf bank_mask:0xf bound_ctrl:1
	v_pk_fma_f32 v[86:87], v[0:1], v[202:203], v[206:207] op_sel_hi:[0,1,1]
	v_pk_fma_f32 v[84:85], v[0:1], v[204:205], v[208:209] op_sel_hi:[0,1,1]
	v_pk_mul_f32 v[186:187], v[86:87], v[210:211]
	s_nop 0
	v_pk_fma_f32 v[186:187], v[84:85], v[212:213], v[186:187]
	s_nop 0
	v_add_f32_e32 v219, v186, v187
	ds_write2st64_b32 v98, v218, v219 offset0:120 offset1:124
